# c8: b_gate vectors loaded once per tile in the in-proj elementwise epilogue
# speedup vs baseline: 1.0358x; 1.0104x over previous
; __device__ __forceinline__ float siluf(float v) { return v * __builtin_amdgcn_rcpf(1.f + __builtin_amdgcn_exp2f(-1.4426950408889634f * v)); }
; __device__ __forceinline__ float sigmf(float v) { return __builtin_amdgcn_rcpf(1.f + __builtin_amdgcn_exp2f(-1.4426950408889634f * v)); }
; #define G1_STG(mi_, ni_, v_) do { const int r_ = (mi_) * 16 + idx; const f32x4 t_ = (v_); u32x2 pk_; pk_.x = pk2(t_.x, t_.y); pk_.y = pk2(t_.z, t_.w); \
;         *(u32x2*)(wl + r_ * 128 + ((((ni_) * 2 + (kq >> 1)) ^ (r_ & 7)) * 16) + (kq & 1) * 8) = pk_; } while (0)
; __device__ void gemm1_phase(const Params& p, int l, int hb, unsigned char* smem) {
;     ...
;             int mode;
;             if (cw < 768) { dbase = (bf16_t*)(p.ws + WS_VA); dpitch = 128; dc0 = cw - 640; mode = 0; }
;             else if (cw < 1280) { dbase = (bf16_t*)(p.ws + WS_GA); dpitch = 512; dc0 = cw - 768; mode = 1; }
;             else if (cw < 3840) { dbase = (bf16_t*)(p.ws + WS_GB); dpitch = 256; dc0 = cw - 3584; mode = 1; }
;             else if (cw < 4864) { dbase = (bf16_t*)(p.ws + WS_XBC); dpitch = 1024; dc0 = cw - 3840; mode = 0; }
;             else if (cw < 5376) { dbase = (bf16_t*)(p.ws + WS_ZS); dpitch = 512; dc0 = cw - 4864; mode = 1; }
;             else { dbase = (bf16_t*)(p.ws + WS_MG); dpitch = 3072; dc0 = cw - 5376; mode = 2; }
;             const float* bg = p.b_gate + l * 3072 + dc0 + lc;
; #pragma unroll
;             for (int mi = 0; mi < 8; ++mi) {
; #pragma unroll
;                 for (int ni = 0; ni < 4; ++ni) {
;                     f32x4 v = acc[mi][ni];
;                     if (mode == 1) { v.x = siluf(v.x); v.y = siluf(v.y); v.z = siluf(v.z); v.w = siluf(v.w); }
;                     else if (mode == 2) { const f32x4 bb = *(const f32x4*)(bg + ni * 16); v.x = sigmf(v.x + bb.x); v.y = sigmf(v.y + bb.y); v.z = sigmf(v.z + bb.z); v.w = sigmf(v.w + bb.w); }
;                     G1_STG(mi, ni, v);
.LBB0_271:
	s_add_i32 s58, s9, s54
	s_ashr_i32 s59, s58, 31
	s_xor_b64 s[62:63], s[38:39], -1
	s_lshl_b64 s[16:17], s[58:59], 2
	s_add_u32 s16, s25, s16
	s_addc_u32 s17, s51, s17
	v_lshlrev_b32_e32 v80, 2, v157
	v_lshl_add_u64 v[130:131], s[16:17], 0, v[80:81]
	global_load_dwordx4 v[160:163], v[130:131], off
	global_load_dwordx4 v[164:167], v[130:131], off offset:64
	global_load_dwordx4 v[168:171], v[130:131], off offset:128
	global_load_dwordx4 v[172:175], v[130:131], off offset:192
	v_cndmask_b32_e64 v80, 0, 1, s[36:37]
	s_mov_b64 s[66:67], -1
	s_and_b64 vcc, exec, s[62:63]
	v_cmp_ne_u32_e64 s[36:37], 1, v80
	s_cbranch_vccz .LBB0_275
	s_and_b64 vcc, exec, s[36:37]
	v_mov_b32_e32 v133, v129
	v_mov_b32_e32 v132, v128
	v_mov_b32_e32 v135, v127
	v_mov_b32_e32 v134, v126
	s_cbranch_vccnz .LBB0_274
	s_waitcnt vmcnt(0)
	v_mov_b32_e32 v132, v160
	v_mov_b32_e32 v133, v161
	v_mov_b32_e32 v134, v162
	v_mov_b32_e32 v135, v163
	v_add_f32_e32 v80, v126, v132
	v_add_f32_e32 v132, v127, v133
	v_add_f32_e32 v133, v128, v134
	v_add_f32_e32 v134, v129, v135
	v_mul_f32_e32 v80, 0xbfb8aa3b, v80
	v_mul_f32_e32 v132, 0xbfb8aa3b, v132
	v_mul_f32_e32 v133, 0xbfb8aa3b, v133
	v_mul_f32_e32 v134, 0xbfb8aa3b, v134
	v_exp_f32_e32 v80, v80
	v_exp_f32_e32 v132, v132
	v_exp_f32_e32 v133, v133
	v_exp_f32_e32 v134, v134
	v_add_f32_e32 v80, 1.0, v80
	v_add_f32_e32 v132, 1.0, v132
	v_add_f32_e32 v133, 1.0, v133
	v_add_f32_e32 v136, 1.0, v134
	v_rcp_f32_e32 v134, v80
	v_rcp_f32_e32 v135, v132
	v_rcp_f32_e32 v132, v133
	v_rcp_f32_e32 v133, v136

; __device__ __forceinline__ float siluf(float v) { return v * __builtin_amdgcn_rcpf(1.f + __builtin_amdgcn_exp2f(-1.4426950408889634f * v)); }
; __device__ __forceinline__ float sigmf(float v) { return __builtin_amdgcn_rcpf(1.f + __builtin_amdgcn_exp2f(-1.4426950408889634f * v)); }
; #define G1_STG(mi_, ni_, v_) do { const int r_ = (mi_) * 16 + idx; const f32x4 t_ = (v_); u32x2 pk_; pk_.x = pk2(t_.x, t_.y); pk_.y = pk2(t_.z, t_.w); \
;         *(u32x2*)(wl + r_ * 128 + ((((ni_) * 2 + (kq >> 1)) ^ (r_ & 7)) * 16) + (kq & 1) * 8) = pk_; } while (0)
; __device__ void gemm1_phase(const Params& p, int l, int hb, unsigned char* smem) {
;     ...
;             for (int mi = 0; mi < 8; ++mi) {
; #pragma unroll
;                 for (int ni = 0; ni < 4; ++ni) {
;                     f32x4 v = acc[mi][ni];
;                     if (mode == 1) { v.x = siluf(v.x); v.y = siluf(v.y); v.z = siluf(v.z); v.w = siluf(v.w); }
;                     else if (mode == 2) { const f32x4 bb = *(const f32x4*)(bg + ni * 16); v.x = sigmf(v.x + bb.x); v.y = sigmf(v.y + bb.y); v.z = sigmf(v.z + bb.z); v.w = sigmf(v.w + bb.w); }
;                     G1_STG(mi, ni, v);
.LBB0_277:
	v_lshlrev_b32_e32 v136, 3, v156
	v_lshlrev_b32_e32 v80, 7, v231
	v_lshrrev_b32_e32 v138, 5, v230
	v_and_b32_e32 v136, 8, v136
	v_add3_u32 v139, s61, v80, v136
	v_bitop3_b32 v80, v138, v181, 7 bitop3:0x78
	v_cvt_pk_bf16_f32 v134, v134, v135
	v_cvt_pk_bf16_f32 v135, v132, v133
	v_lshlrev_b32_e32 v80, 4, v80
	v_cndmask_b32_e64 v132, 0, 1, s[62:63]
	v_readlane_b32 s66, v255, 56
	v_add_u32_e32 v80, v139, v80
	v_cmp_ne_u32_e64 s[38:39], 1, v132
	s_andn2_b64 vcc, exec, s[62:63]
	s_mov_b64 s[62:63], -1
	v_readlane_b32 s67, v255, 57
	ds_write_b64 v80, v[134:135]
	s_cbranch_vccnz .LBB0_281
	s_and_b64 vcc, exec, s[36:37]
	v_mov_b32_e32 v133, v125
	v_mov_b32_e32 v132, v124
	v_mov_b32_e32 v135, v123
	v_mov_b32_e32 v134, v122
	s_cbranch_vccnz .LBB0_280
	s_waitcnt vmcnt(0)
	v_mov_b32_e32 v132, v164
	v_mov_b32_e32 v133, v165
	v_mov_b32_e32 v134, v166
	v_mov_b32_e32 v135, v167
	v_add_f32_e32 v132, v122, v132
	v_add_f32_e32 v133, v123, v133
	v_add_f32_e32 v134, v124, v134
	v_add_f32_e32 v135, v125, v135
	v_mul_f32_e32 v132, 0xbfb8aa3b, v132
	v_mul_f32_e32 v133, 0xbfb8aa3b, v133
	v_mul_f32_e32 v134, 0xbfb8aa3b, v134
	v_mul_f32_e32 v135, 0xbfb8aa3b, v135
	v_exp_f32_e32 v132, v132
	v_exp_f32_e32 v133, v133
	v_exp_f32_e32 v134, v134
	v_exp_f32_e32 v135, v135
	v_add_f32_e32 v132, 1.0, v132
	v_add_f32_e32 v133, 1.0, v133
	v_add_f32_e32 v136, 1.0, v134
	v_add_f32_e32 v137, 1.0, v135
	v_rcp_f32_e32 v134, v132
	v_rcp_f32_e32 v135, v133
	v_rcp_f32_e32 v132, v136
	v_rcp_f32_e32 v133, v137

; __device__ __forceinline__ float siluf(float v) { return v * __builtin_amdgcn_rcpf(1.f + __builtin_amdgcn_exp2f(-1.4426950408889634f * v)); }
; __device__ __forceinline__ float sigmf(float v) { return __builtin_amdgcn_rcpf(1.f + __builtin_amdgcn_exp2f(-1.4426950408889634f * v)); }
; #define G1_STG(mi_, ni_, v_) do { const int r_ = (mi_) * 16 + idx; const f32x4 t_ = (v_); u32x2 pk_; pk_.x = pk2(t_.x, t_.y); pk_.y = pk2(t_.z, t_.w); \
;         *(u32x2*)(wl + r_ * 128 + ((((ni_) * 2 + (kq >> 1)) ^ (r_ & 7)) * 16) + (kq & 1) * 8) = pk_; } while (0)
; __device__ void gemm1_phase(const Params& p, int l, int hb, unsigned char* smem) {
;     ...
;             for (int mi = 0; mi < 8; ++mi) {
; #pragma unroll
;                 for (int ni = 0; ni < 4; ++ni) {
;                     f32x4 v = acc[mi][ni];
;                     if (mode == 1) { v.x = siluf(v.x); v.y = siluf(v.y); v.z = siluf(v.z); v.w = siluf(v.w); }
;                     else if (mode == 2) { const f32x4 bb = *(const f32x4*)(bg + ni * 16); v.x = sigmf(v.x + bb.x); v.y = sigmf(v.y + bb.y); v.z = sigmf(v.z + bb.z); v.w = sigmf(v.w + bb.w); }
;                     G1_STG(mi, ni, v);
.LBB0_283:
	v_and_b32_e32 v140, 7, v181
	v_cvt_pk_bf16_f32 v134, v134, v135
	v_cvt_pk_bf16_f32 v135, v132, v133
	v_bitop3_b32 v132, v138, v140, 2 bitop3:0x36
	v_lshlrev_b32_e32 v132, 4, v132
	v_add_u32_e32 v136, v139, v132
	s_and_b64 vcc, exec, s[38:39]
	s_mov_b64 s[62:63], -1
	ds_write_b64 v136, v[134:135]
	s_cbranch_vccnz .LBB0_287
	s_and_b64 vcc, exec, s[36:37]
	v_mov_b32_e32 v133, v121
	v_mov_b32_e32 v132, v120
	v_mov_b32_e32 v135, v119
	v_mov_b32_e32 v134, v118
	s_cbranch_vccnz .LBB0_286
	s_waitcnt vmcnt(0)
	v_mov_b32_e32 v132, v168
	v_mov_b32_e32 v133, v169
	v_mov_b32_e32 v134, v170
	v_mov_b32_e32 v135, v171
	v_add_f32_e32 v132, v118, v132
	v_add_f32_e32 v133, v119, v133
	v_add_f32_e32 v134, v120, v134
	v_add_f32_e32 v135, v121, v135
	v_mul_f32_e32 v132, 0xbfb8aa3b, v132
	v_mul_f32_e32 v133, 0xbfb8aa3b, v133
	v_mul_f32_e32 v134, 0xbfb8aa3b, v134
	v_mul_f32_e32 v135, 0xbfb8aa3b, v135
	v_exp_f32_e32 v132, v132
	v_exp_f32_e32 v133, v133
	v_exp_f32_e32 v134, v134
	v_exp_f32_e32 v135, v135
	v_add_f32_e32 v132, 1.0, v132
	v_add_f32_e32 v133, 1.0, v133
	v_add_f32_e32 v137, 1.0, v134
	v_add_f32_e32 v141, 1.0, v135
	v_rcp_f32_e32 v134, v132
	v_rcp_f32_e32 v135, v133
	v_rcp_f32_e32 v132, v137
	v_rcp_f32_e32 v133, v141

; __device__ __forceinline__ float siluf(float v) { return v * __builtin_amdgcn_rcpf(1.f + __builtin_amdgcn_exp2f(-1.4426950408889634f * v)); }
; __device__ __forceinline__ float sigmf(float v) { return __builtin_amdgcn_rcpf(1.f + __builtin_amdgcn_exp2f(-1.4426950408889634f * v)); }
; #define G1_STG(mi_, ni_, v_) do { const int r_ = (mi_) * 16 + idx; const f32x4 t_ = (v_); u32x2 pk_; pk_.x = pk2(t_.x, t_.y); pk_.y = pk2(t_.z, t_.w); \
;         *(u32x2*)(wl + r_ * 128 + ((((ni_) * 2 + (kq >> 1)) ^ (r_ & 7)) * 16) + (kq & 1) * 8) = pk_; } while (0)
; __device__ void gemm1_phase(const Params& p, int l, int hb, unsigned char* smem) {
;     ...
;             for (int mi = 0; mi < 8; ++mi) {
; #pragma unroll
;                 for (int ni = 0; ni < 4; ++ni) {
;                     f32x4 v = acc[mi][ni];
;                     if (mode == 1) { v.x = siluf(v.x); v.y = siluf(v.y); v.z = siluf(v.z); v.w = siluf(v.w); }
;                     else if (mode == 2) { const f32x4 bb = *(const f32x4*)(bg + ni * 16); v.x = sigmf(v.x + bb.x); v.y = sigmf(v.y + bb.y); v.z = sigmf(v.z + bb.z); v.w = sigmf(v.w + bb.w); }
;                     G1_STG(mi, ni, v);
.LBB0_289:
	s_nop 0
	v_cvt_pk_bf16_f32 v134, v134, v135
	v_cvt_pk_bf16_f32 v135, v132, v133
	v_bitop3_b32 v132, v138, v140, 4 bitop3:0x36
	v_lshlrev_b32_e32 v132, 4, v132
	v_add_u32_e32 v137, v139, v132
	s_and_b64 vcc, exec, s[38:39]
	s_mov_b64 s[62:63], -1
	ds_write_b64 v137, v[134:135]
	s_cbranch_vccnz .LBB0_293
	s_and_b64 vcc, exec, s[36:37]
	v_mov_b32_e32 v133, v117
	v_mov_b32_e32 v132, v116
	v_mov_b32_e32 v135, v115
	v_mov_b32_e32 v134, v114
	s_cbranch_vccnz .LBB0_292
	s_waitcnt vmcnt(0)
	v_mov_b32_e32 v132, v172
	v_mov_b32_e32 v133, v173
	v_mov_b32_e32 v134, v174
	v_mov_b32_e32 v135, v175
	v_add_f32_e32 v132, v114, v132
	v_add_f32_e32 v133, v115, v133
	v_add_f32_e32 v134, v116, v134
	v_add_f32_e32 v135, v117, v135
	v_mul_f32_e32 v132, 0xbfb8aa3b, v132
	v_mul_f32_e32 v133, 0xbfb8aa3b, v133
	v_mul_f32_e32 v134, 0xbfb8aa3b, v134
	v_mul_f32_e32 v135, 0xbfb8aa3b, v135
	v_exp_f32_e32 v132, v132
	v_exp_f32_e32 v133, v133
	v_exp_f32_e32 v134, v134
	v_exp_f32_e32 v135, v135
	v_add_f32_e32 v132, 1.0, v132
	v_add_f32_e32 v133, 1.0, v133
	v_add_f32_e32 v141, 1.0, v134
	v_add_f32_e32 v142, 1.0, v135
	v_rcp_f32_e32 v134, v132
	v_rcp_f32_e32 v135, v133
	v_rcp_f32_e32 v132, v141
	v_rcp_f32_e32 v133, v142

; __device__ __forceinline__ float siluf(float v) { return v * __builtin_amdgcn_rcpf(1.f + __builtin_amdgcn_exp2f(-1.4426950408889634f * v)); }
; __device__ __forceinline__ float sigmf(float v) { return __builtin_amdgcn_rcpf(1.f + __builtin_amdgcn_exp2f(-1.4426950408889634f * v)); }
; #define G1_STG(mi_, ni_, v_) do { const int r_ = (mi_) * 16 + idx; const f32x4 t_ = (v_); u32x2 pk_; pk_.x = pk2(t_.x, t_.y); pk_.y = pk2(t_.z, t_.w); \
;         *(u32x2*)(wl + r_ * 128 + ((((ni_) * 2 + (kq >> 1)) ^ (r_ & 7)) * 16) + (kq & 1) * 8) = pk_; } while (0)
; __device__ void gemm1_phase(const Params& p, int l, int hb, unsigned char* smem) {
;     ...
;             for (int mi = 0; mi < 8; ++mi) {
; #pragma unroll
;                 for (int ni = 0; ni < 4; ++ni) {
;                     f32x4 v = acc[mi][ni];
;                     if (mode == 1) { v.x = siluf(v.x); v.y = siluf(v.y); v.z = siluf(v.z); v.w = siluf(v.w); }
;                     else if (mode == 2) { const f32x4 bb = *(const f32x4*)(bg + ni * 16); v.x = sigmf(v.x + bb.x); v.y = sigmf(v.y + bb.y); v.z = sigmf(v.z + bb.z); v.w = sigmf(v.w + bb.w); }
;                     G1_STG(mi, ni, v);
.LBB0_295:
	s_nop 0
	v_cvt_pk_bf16_f32 v134, v134, v135
	v_cvt_pk_bf16_f32 v135, v132, v133
	v_bitop3_b32 v132, v138, v140, 6 bitop3:0x36
	v_lshlrev_b32_e32 v132, 4, v132
	v_add_u32_e32 v138, v139, v132
	s_and_b64 vcc, exec, s[38:39]
	s_mov_b64 s[62:63], -1
	ds_write_b64 v138, v[134:135]
	s_cbranch_vccnz .LBB0_299
	s_and_b64 vcc, exec, s[36:37]
	v_mov_b32_e32 v133, v113
	v_mov_b32_e32 v132, v112
	v_mov_b32_e32 v135, v111
	v_mov_b32_e32 v134, v110
	s_cbranch_vccnz .LBB0_298
	s_waitcnt vmcnt(0)
	v_mov_b32_e32 v132, v160
	v_mov_b32_e32 v133, v161
	v_mov_b32_e32 v134, v162
	v_mov_b32_e32 v135, v163
	v_add_f32_e32 v132, v110, v132
	v_add_f32_e32 v133, v111, v133
	v_add_f32_e32 v134, v112, v134
	v_add_f32_e32 v135, v113, v135
	v_mul_f32_e32 v132, 0xbfb8aa3b, v132
	v_mul_f32_e32 v133, 0xbfb8aa3b, v133
	v_mul_f32_e32 v134, 0xbfb8aa3b, v134
	v_mul_f32_e32 v135, 0xbfb8aa3b, v135
	v_exp_f32_e32 v132, v132
	v_exp_f32_e32 v133, v133
	v_exp_f32_e32 v134, v134
	v_exp_f32_e32 v135, v135
	v_add_f32_e32 v132, 1.0, v132
	v_add_f32_e32 v133, 1.0, v133
	v_add_f32_e32 v139, 1.0, v134
	v_add_f32_e32 v140, 1.0, v135
	v_rcp_f32_e32 v134, v132
	v_rcp_f32_e32 v135, v133
	v_rcp_f32_e32 v132, v139
	v_rcp_f32_e32 v133, v140

; __device__ __forceinline__ float siluf(float v) { return v * __builtin_amdgcn_rcpf(1.f + __builtin_amdgcn_exp2f(-1.4426950408889634f * v)); }
; __device__ __forceinline__ float sigmf(float v) { return __builtin_amdgcn_rcpf(1.f + __builtin_amdgcn_exp2f(-1.4426950408889634f * v)); }
; #define G1_STG(mi_, ni_, v_) do { const int r_ = (mi_) * 16 + idx; const f32x4 t_ = (v_); u32x2 pk_; pk_.x = pk2(t_.x, t_.y); pk_.y = pk2(t_.z, t_.w); \
;         *(u32x2*)(wl + r_ * 128 + ((((ni_) * 2 + (kq >> 1)) ^ (r_ & 7)) * 16) + (kq & 1) * 8) = pk_; } while (0)
; __device__ void gemm1_phase(const Params& p, int l, int hb, unsigned char* smem) {
;     ...
;             for (int mi = 0; mi < 8; ++mi) {
; #pragma unroll
;                 for (int ni = 0; ni < 4; ++ni) {
;                     f32x4 v = acc[mi][ni];
;                     if (mode == 1) { v.x = siluf(v.x); v.y = siluf(v.y); v.z = siluf(v.z); v.w = siluf(v.w); }
;                     else if (mode == 2) { const f32x4 bb = *(const f32x4*)(bg + ni * 16); v.x = sigmf(v.x + bb.x); v.y = sigmf(v.y + bb.y); v.z = sigmf(v.z + bb.z); v.w = sigmf(v.w + bb.w); }
;                     G1_STG(mi, ni, v);
.LBB0_301:
	s_nop 0
	v_cvt_pk_bf16_f32 v134, v134, v135
	v_cvt_pk_bf16_f32 v135, v132, v133
	s_and_b64 vcc, exec, s[38:39]
	s_mov_b64 s[62:63], -1
	ds_write_b64 v80, v[134:135] offset:2048
	s_cbranch_vccnz .LBB0_305
	s_and_b64 vcc, exec, s[36:37]
	v_mov_b32_e32 v133, v109
	v_mov_b32_e32 v132, v108
	v_mov_b32_e32 v135, v107
	v_mov_b32_e32 v134, v106
	s_cbranch_vccnz .LBB0_304
	s_waitcnt vmcnt(0)
	v_mov_b32_e32 v132, v164
	v_mov_b32_e32 v133, v165
	v_mov_b32_e32 v134, v166
	v_mov_b32_e32 v135, v167
	v_add_f32_e32 v132, v106, v132
	v_add_f32_e32 v133, v107, v133
	v_add_f32_e32 v134, v108, v134
	v_add_f32_e32 v135, v109, v135
	v_mul_f32_e32 v132, 0xbfb8aa3b, v132
	v_mul_f32_e32 v133, 0xbfb8aa3b, v133
	v_mul_f32_e32 v134, 0xbfb8aa3b, v134
	v_mul_f32_e32 v135, 0xbfb8aa3b, v135
	v_exp_f32_e32 v132, v132
	v_exp_f32_e32 v133, v133
	v_exp_f32_e32 v134, v134
	v_exp_f32_e32 v135, v135
	v_add_f32_e32 v132, 1.0, v132
	v_add_f32_e32 v133, 1.0, v133
	v_add_f32_e32 v139, 1.0, v134
	v_add_f32_e32 v140, 1.0, v135
	v_rcp_f32_e32 v134, v132
	v_rcp_f32_e32 v135, v133
	v_rcp_f32_e32 v132, v139
	v_rcp_f32_e32 v133, v140

; __device__ __forceinline__ float siluf(float v) { return v * __builtin_amdgcn_rcpf(1.f + __builtin_amdgcn_exp2f(-1.4426950408889634f * v)); }
; __device__ __forceinline__ float sigmf(float v) { return __builtin_amdgcn_rcpf(1.f + __builtin_amdgcn_exp2f(-1.4426950408889634f * v)); }
; #define G1_STG(mi_, ni_, v_) do { const int r_ = (mi_) * 16 + idx; const f32x4 t_ = (v_); u32x2 pk_; pk_.x = pk2(t_.x, t_.y); pk_.y = pk2(t_.z, t_.w); \
;         *(u32x2*)(wl + r_ * 128 + ((((ni_) * 2 + (kq >> 1)) ^ (r_ & 7)) * 16) + (kq & 1) * 8) = pk_; } while (0)
; __device__ void gemm1_phase(const Params& p, int l, int hb, unsigned char* smem) {
;     ...
;             for (int mi = 0; mi < 8; ++mi) {
; #pragma unroll
;                 for (int ni = 0; ni < 4; ++ni) {
;                     f32x4 v = acc[mi][ni];
;                     if (mode == 1) { v.x = siluf(v.x); v.y = siluf(v.y); v.z = siluf(v.z); v.w = siluf(v.w); }
;                     else if (mode == 2) { const f32x4 bb = *(const f32x4*)(bg + ni * 16); v.x = sigmf(v.x + bb.x); v.y = sigmf(v.y + bb.y); v.z = sigmf(v.z + bb.z); v.w = sigmf(v.w + bb.w); }
;                     G1_STG(mi, ni, v);
.LBB0_307:
	s_nop 0
	v_cvt_pk_bf16_f32 v134, v134, v135
	v_cvt_pk_bf16_f32 v135, v132, v133
	s_and_b64 vcc, exec, s[38:39]
	s_mov_b64 s[62:63], -1
	ds_write_b64 v136, v[134:135] offset:2048
	s_cbranch_vccnz .LBB0_311
	s_and_b64 vcc, exec, s[36:37]
	v_mov_b32_e32 v133, v105
	v_mov_b32_e32 v132, v104
	v_mov_b32_e32 v135, v103
	v_mov_b32_e32 v134, v102
	s_cbranch_vccnz .LBB0_310
	s_waitcnt vmcnt(0)
	v_mov_b32_e32 v132, v168
	v_mov_b32_e32 v133, v169
	v_mov_b32_e32 v134, v170
	v_mov_b32_e32 v135, v171
	v_add_f32_e32 v132, v102, v132
	v_add_f32_e32 v133, v103, v133
	v_add_f32_e32 v134, v104, v134
	v_add_f32_e32 v135, v105, v135
	v_mul_f32_e32 v132, 0xbfb8aa3b, v132
	v_mul_f32_e32 v133, 0xbfb8aa3b, v133
	v_mul_f32_e32 v134, 0xbfb8aa3b, v134
	v_mul_f32_e32 v135, 0xbfb8aa3b, v135
	v_exp_f32_e32 v132, v132
	v_exp_f32_e32 v133, v133
	v_exp_f32_e32 v134, v134
	v_exp_f32_e32 v135, v135
	v_add_f32_e32 v132, 1.0, v132
	v_add_f32_e32 v133, 1.0, v133
	v_add_f32_e32 v139, 1.0, v134
	v_add_f32_e32 v140, 1.0, v135
	v_rcp_f32_e32 v134, v132
	v_rcp_f32_e32 v135, v133
	v_rcp_f32_e32 v132, v139
	v_rcp_f32_e32 v133, v140

; __device__ __forceinline__ float siluf(float v) { return v * __builtin_amdgcn_rcpf(1.f + __builtin_amdgcn_exp2f(-1.4426950408889634f * v)); }
; __device__ __forceinline__ float sigmf(float v) { return __builtin_amdgcn_rcpf(1.f + __builtin_amdgcn_exp2f(-1.4426950408889634f * v)); }
; #define G1_STG(mi_, ni_, v_) do { const int r_ = (mi_) * 16 + idx; const f32x4 t_ = (v_); u32x2 pk_; pk_.x = pk2(t_.x, t_.y); pk_.y = pk2(t_.z, t_.w); \
;         *(u32x2*)(wl + r_ * 128 + ((((ni_) * 2 + (kq >> 1)) ^ (r_ & 7)) * 16) + (kq & 1) * 8) = pk_; } while (0)
; __device__ void gemm1_phase(const Params& p, int l, int hb, unsigned char* smem) {
;     ...
;             for (int mi = 0; mi < 8; ++mi) {
; #pragma unroll
;                 for (int ni = 0; ni < 4; ++ni) {
;                     f32x4 v = acc[mi][ni];
;                     if (mode == 1) { v.x = siluf(v.x); v.y = siluf(v.y); v.z = siluf(v.z); v.w = siluf(v.w); }
;                     else if (mode == 2) { const f32x4 bb = *(const f32x4*)(bg + ni * 16); v.x = sigmf(v.x + bb.x); v.y = sigmf(v.y + bb.y); v.z = sigmf(v.z + bb.z); v.w = sigmf(v.w + bb.w); }
;                     G1_STG(mi, ni, v);
.LBB0_313:
	s_nop 0
	v_cvt_pk_bf16_f32 v134, v134, v135
	v_cvt_pk_bf16_f32 v135, v132, v133
	s_and_b64 vcc, exec, s[38:39]
	s_mov_b64 s[62:63], -1
	ds_write_b64 v137, v[134:135] offset:2048
	s_cbranch_vccnz .LBB0_317
	s_and_b64 vcc, exec, s[36:37]
	v_mov_b32_e32 v133, v101
	v_mov_b32_e32 v132, v100
	v_mov_b32_e32 v135, v99
	v_mov_b32_e32 v134, v98
	s_cbranch_vccnz .LBB0_316
	s_waitcnt vmcnt(0)
	v_mov_b32_e32 v132, v172
	v_mov_b32_e32 v133, v173
	v_mov_b32_e32 v134, v174
	v_mov_b32_e32 v135, v175
	v_add_f32_e32 v132, v98, v132
	v_add_f32_e32 v133, v99, v133
	v_add_f32_e32 v134, v100, v134
	v_add_f32_e32 v135, v101, v135
	v_mul_f32_e32 v132, 0xbfb8aa3b, v132
	v_mul_f32_e32 v133, 0xbfb8aa3b, v133
	v_mul_f32_e32 v134, 0xbfb8aa3b, v134
	v_mul_f32_e32 v135, 0xbfb8aa3b, v135
	v_exp_f32_e32 v132, v132
	v_exp_f32_e32 v133, v133
	v_exp_f32_e32 v134, v134
	v_exp_f32_e32 v135, v135
	v_add_f32_e32 v132, 1.0, v132
	v_add_f32_e32 v133, 1.0, v133
	v_add_f32_e32 v139, 1.0, v134
	v_add_f32_e32 v140, 1.0, v135
	v_rcp_f32_e32 v134, v132
	v_rcp_f32_e32 v135, v133
	v_rcp_f32_e32 v132, v139
	v_rcp_f32_e32 v133, v140

; __device__ __forceinline__ float siluf(float v) { return v * __builtin_amdgcn_rcpf(1.f + __builtin_amdgcn_exp2f(-1.4426950408889634f * v)); }
; __device__ __forceinline__ float sigmf(float v) { return __builtin_amdgcn_rcpf(1.f + __builtin_amdgcn_exp2f(-1.4426950408889634f * v)); }
; #define G1_STG(mi_, ni_, v_) do { const int r_ = (mi_) * 16 + idx; const f32x4 t_ = (v_); u32x2 pk_; pk_.x = pk2(t_.x, t_.y); pk_.y = pk2(t_.z, t_.w); \
;         *(u32x2*)(wl + r_ * 128 + ((((ni_) * 2 + (kq >> 1)) ^ (r_ & 7)) * 16) + (kq & 1) * 8) = pk_; } while (0)
; __device__ void gemm1_phase(const Params& p, int l, int hb, unsigned char* smem) {
;     ...
;             for (int mi = 0; mi < 8; ++mi) {
; #pragma unroll
;                 for (int ni = 0; ni < 4; ++ni) {
;                     f32x4 v = acc[mi][ni];
;                     if (mode == 1) { v.x = siluf(v.x); v.y = siluf(v.y); v.z = siluf(v.z); v.w = siluf(v.w); }
;                     else if (mode == 2) { const f32x4 bb = *(const f32x4*)(bg + ni * 16); v.x = sigmf(v.x + bb.x); v.y = sigmf(v.y + bb.y); v.z = sigmf(v.z + bb.z); v.w = sigmf(v.w + bb.w); }
;                     G1_STG(mi, ni, v);
.LBB0_319:
	s_nop 0
	v_cvt_pk_bf16_f32 v134, v134, v135
	v_cvt_pk_bf16_f32 v135, v132, v133
	s_and_b64 vcc, exec, s[38:39]
	s_mov_b64 s[62:63], -1
	ds_write_b64 v138, v[134:135] offset:2048
	s_cbranch_vccnz .LBB0_323
	s_and_b64 vcc, exec, s[36:37]
	v_mov_b32_e32 v133, v97
	v_mov_b32_e32 v132, v96
	v_mov_b32_e32 v135, v95
	v_mov_b32_e32 v134, v94
	s_cbranch_vccnz .LBB0_322
	s_waitcnt vmcnt(0)
	v_mov_b32_e32 v132, v160
	v_mov_b32_e32 v133, v161
	v_mov_b32_e32 v134, v162
	v_mov_b32_e32 v135, v163
	v_add_f32_e32 v132, v94, v132
	v_add_f32_e32 v133, v95, v133
	v_add_f32_e32 v134, v96, v134
	v_add_f32_e32 v135, v97, v135
	v_mul_f32_e32 v132, 0xbfb8aa3b, v132
	v_mul_f32_e32 v133, 0xbfb8aa3b, v133
	v_mul_f32_e32 v134, 0xbfb8aa3b, v134
	v_mul_f32_e32 v135, 0xbfb8aa3b, v135
	v_exp_f32_e32 v132, v132
	v_exp_f32_e32 v133, v133
	v_exp_f32_e32 v134, v134
	v_exp_f32_e32 v135, v135
	v_add_f32_e32 v132, 1.0, v132
	v_add_f32_e32 v133, 1.0, v133
	v_add_f32_e32 v139, 1.0, v134
	v_add_f32_e32 v140, 1.0, v135
	v_rcp_f32_e32 v134, v132
	v_rcp_f32_e32 v135, v133
	v_rcp_f32_e32 v132, v139
	v_rcp_f32_e32 v133, v140

; __device__ __forceinline__ float siluf(float v) { return v * __builtin_amdgcn_rcpf(1.f + __builtin_amdgcn_exp2f(-1.4426950408889634f * v)); }
; __device__ __forceinline__ float sigmf(float v) { return __builtin_amdgcn_rcpf(1.f + __builtin_amdgcn_exp2f(-1.4426950408889634f * v)); }
; #define G1_STG(mi_, ni_, v_) do { const int r_ = (mi_) * 16 + idx; const f32x4 t_ = (v_); u32x2 pk_; pk_.x = pk2(t_.x, t_.y); pk_.y = pk2(t_.z, t_.w); \
;         *(u32x2*)(wl + r_ * 128 + ((((ni_) * 2 + (kq >> 1)) ^ (r_ & 7)) * 16) + (kq & 1) * 8) = pk_; } while (0)
; __device__ void gemm1_phase(const Params& p, int l, int hb, unsigned char* smem) {
;     ...
;             for (int mi = 0; mi < 8; ++mi) {
; #pragma unroll
;                 for (int ni = 0; ni < 4; ++ni) {
;                     f32x4 v = acc[mi][ni];
;                     if (mode == 1) { v.x = siluf(v.x); v.y = siluf(v.y); v.z = siluf(v.z); v.w = siluf(v.w); }
;                     else if (mode == 2) { const f32x4 bb = *(const f32x4*)(bg + ni * 16); v.x = sigmf(v.x + bb.x); v.y = sigmf(v.y + bb.y); v.z = sigmf(v.z + bb.z); v.w = sigmf(v.w + bb.w); }
;                     G1_STG(mi, ni, v);
.LBB0_325:
	s_nop 0
	v_cvt_pk_bf16_f32 v134, v134, v135
	v_cvt_pk_bf16_f32 v135, v132, v133
	s_and_b64 vcc, exec, s[38:39]
	s_mov_b64 s[62:63], -1
	ds_write_b64 v80, v[134:135] offset:4096
	s_cbranch_vccnz .LBB0_329
	s_and_b64 vcc, exec, s[36:37]
	v_mov_b32_e32 v133, v93
	v_mov_b32_e32 v132, v92
	v_mov_b32_e32 v135, v91
	v_mov_b32_e32 v134, v90
	s_cbranch_vccnz .LBB0_328
	s_waitcnt vmcnt(0)
	v_mov_b32_e32 v132, v164
	v_mov_b32_e32 v133, v165
	v_mov_b32_e32 v134, v166
	v_mov_b32_e32 v135, v167
	v_add_f32_e32 v132, v90, v132
	v_add_f32_e32 v133, v91, v133
	v_add_f32_e32 v134, v92, v134
	v_add_f32_e32 v135, v93, v135
	v_mul_f32_e32 v132, 0xbfb8aa3b, v132
	v_mul_f32_e32 v133, 0xbfb8aa3b, v133
	v_mul_f32_e32 v134, 0xbfb8aa3b, v134
	v_mul_f32_e32 v135, 0xbfb8aa3b, v135
	v_exp_f32_e32 v132, v132
	v_exp_f32_e32 v133, v133
	v_exp_f32_e32 v134, v134
	v_exp_f32_e32 v135, v135
	v_add_f32_e32 v132, 1.0, v132
	v_add_f32_e32 v133, 1.0, v133
	v_add_f32_e32 v139, 1.0, v134
	v_add_f32_e32 v140, 1.0, v135
	v_rcp_f32_e32 v134, v132
	v_rcp_f32_e32 v135, v133
	v_rcp_f32_e32 v132, v139
	v_rcp_f32_e32 v133, v140

; __device__ __forceinline__ float siluf(float v) { return v * __builtin_amdgcn_rcpf(1.f + __builtin_amdgcn_exp2f(-1.4426950408889634f * v)); }
; __device__ __forceinline__ float sigmf(float v) { return __builtin_amdgcn_rcpf(1.f + __builtin_amdgcn_exp2f(-1.4426950408889634f * v)); }
; #define G1_STG(mi_, ni_, v_) do { const int r_ = (mi_) * 16 + idx; const f32x4 t_ = (v_); u32x2 pk_; pk_.x = pk2(t_.x, t_.y); pk_.y = pk2(t_.z, t_.w); \
;         *(u32x2*)(wl + r_ * 128 + ((((ni_) * 2 + (kq >> 1)) ^ (r_ & 7)) * 16) + (kq & 1) * 8) = pk_; } while (0)
; __device__ void gemm1_phase(const Params& p, int l, int hb, unsigned char* smem) {
;     ...
;             for (int mi = 0; mi < 8; ++mi) {
; #pragma unroll
;                 for (int ni = 0; ni < 4; ++ni) {
;                     f32x4 v = acc[mi][ni];
;                     if (mode == 1) { v.x = siluf(v.x); v.y = siluf(v.y); v.z = siluf(v.z); v.w = siluf(v.w); }
;                     else if (mode == 2) { const f32x4 bb = *(const f32x4*)(bg + ni * 16); v.x = sigmf(v.x + bb.x); v.y = sigmf(v.y + bb.y); v.z = sigmf(v.z + bb.z); v.w = sigmf(v.w + bb.w); }
;                     G1_STG(mi, ni, v);
.LBB0_331:
	s_nop 0
	v_cvt_pk_bf16_f32 v134, v134, v135
	v_cvt_pk_bf16_f32 v135, v132, v133
	s_and_b64 vcc, exec, s[38:39]
	s_mov_b64 s[62:63], -1
	ds_write_b64 v136, v[134:135] offset:4096
	s_cbranch_vccnz .LBB0_335
	s_and_b64 vcc, exec, s[36:37]
	v_mov_b32_e32 v133, v89
	v_mov_b32_e32 v132, v88
	v_mov_b32_e32 v135, v87
	v_mov_b32_e32 v134, v86
	s_cbranch_vccnz .LBB0_334
	s_waitcnt vmcnt(0)
	v_mov_b32_e32 v132, v168
	v_mov_b32_e32 v133, v169
	v_mov_b32_e32 v134, v170
	v_mov_b32_e32 v135, v171
	v_add_f32_e32 v132, v86, v132
	v_add_f32_e32 v133, v87, v133
	v_add_f32_e32 v134, v88, v134
	v_add_f32_e32 v135, v89, v135
	v_mul_f32_e32 v132, 0xbfb8aa3b, v132
	v_mul_f32_e32 v133, 0xbfb8aa3b, v133
	v_mul_f32_e32 v134, 0xbfb8aa3b, v134
	v_mul_f32_e32 v135, 0xbfb8aa3b, v135
	v_exp_f32_e32 v132, v132
	v_exp_f32_e32 v133, v133
	v_exp_f32_e32 v134, v134
	v_exp_f32_e32 v135, v135
	v_add_f32_e32 v132, 1.0, v132
	v_add_f32_e32 v133, 1.0, v133
	v_add_f32_e32 v139, 1.0, v134
	v_add_f32_e32 v140, 1.0, v135
	v_rcp_f32_e32 v134, v132
	v_rcp_f32_e32 v135, v133
	v_rcp_f32_e32 v132, v139
	v_rcp_f32_e32 v133, v140

; __device__ __forceinline__ float siluf(float v) { return v * __builtin_amdgcn_rcpf(1.f + __builtin_amdgcn_exp2f(-1.4426950408889634f * v)); }
; __device__ __forceinline__ float sigmf(float v) { return __builtin_amdgcn_rcpf(1.f + __builtin_amdgcn_exp2f(-1.4426950408889634f * v)); }
; #define G1_STG(mi_, ni_, v_) do { const int r_ = (mi_) * 16 + idx; const f32x4 t_ = (v_); u32x2 pk_; pk_.x = pk2(t_.x, t_.y); pk_.y = pk2(t_.z, t_.w); \
;         *(u32x2*)(wl + r_ * 128 + ((((ni_) * 2 + (kq >> 1)) ^ (r_ & 7)) * 16) + (kq & 1) * 8) = pk_; } while (0)
; __device__ void gemm1_phase(const Params& p, int l, int hb, unsigned char* smem) {
;     ...
;             for (int mi = 0; mi < 8; ++mi) {
; #pragma unroll
;                 for (int ni = 0; ni < 4; ++ni) {
;                     f32x4 v = acc[mi][ni];
;                     if (mode == 1) { v.x = siluf(v.x); v.y = siluf(v.y); v.z = siluf(v.z); v.w = siluf(v.w); }
;                     else if (mode == 2) { const f32x4 bb = *(const f32x4*)(bg + ni * 16); v.x = sigmf(v.x + bb.x); v.y = sigmf(v.y + bb.y); v.z = sigmf(v.z + bb.z); v.w = sigmf(v.w + bb.w); }
;                     G1_STG(mi, ni, v);
.LBB0_337:
	s_nop 0
	v_cvt_pk_bf16_f32 v134, v134, v135
	v_cvt_pk_bf16_f32 v135, v132, v133
	s_and_b64 vcc, exec, s[38:39]
	s_mov_b64 s[62:63], -1
	ds_write_b64 v137, v[134:135] offset:4096
	s_cbranch_vccnz .LBB0_341
	s_and_b64 vcc, exec, s[36:37]
	v_mov_b32_e32 v133, v85
	v_mov_b32_e32 v132, v84
	v_mov_b32_e32 v135, v83
	v_mov_b32_e32 v134, v82
	s_cbranch_vccnz .LBB0_340
	s_waitcnt vmcnt(0)
	v_mov_b32_e32 v132, v172
	v_mov_b32_e32 v133, v173
	v_mov_b32_e32 v134, v174
	v_mov_b32_e32 v135, v175
	v_add_f32_e32 v132, v82, v132
	v_add_f32_e32 v133, v83, v133
	v_add_f32_e32 v134, v84, v134
	v_add_f32_e32 v135, v85, v135
	v_mul_f32_e32 v132, 0xbfb8aa3b, v132
	v_mul_f32_e32 v133, 0xbfb8aa3b, v133
	v_mul_f32_e32 v134, 0xbfb8aa3b, v134
	v_mul_f32_e32 v135, 0xbfb8aa3b, v135
	v_exp_f32_e32 v132, v132
	v_exp_f32_e32 v133, v133
	v_exp_f32_e32 v134, v134
	v_exp_f32_e32 v135, v135
	v_add_f32_e32 v132, 1.0, v132
	v_add_f32_e32 v133, 1.0, v133
	v_add_f32_e32 v139, 1.0, v134
	v_add_f32_e32 v140, 1.0, v135
	v_rcp_f32_e32 v134, v132
	v_rcp_f32_e32 v135, v133
	v_rcp_f32_e32 v132, v139
	v_rcp_f32_e32 v133, v140

; __device__ __forceinline__ float siluf(float v) { return v * __builtin_amdgcn_rcpf(1.f + __builtin_amdgcn_exp2f(-1.4426950408889634f * v)); }
; __device__ __forceinline__ float sigmf(float v) { return __builtin_amdgcn_rcpf(1.f + __builtin_amdgcn_exp2f(-1.4426950408889634f * v)); }
; #define G1_STG(mi_, ni_, v_) do { const int r_ = (mi_) * 16 + idx; const f32x4 t_ = (v_); u32x2 pk_; pk_.x = pk2(t_.x, t_.y); pk_.y = pk2(t_.z, t_.w); \
;         *(u32x2*)(wl + r_ * 128 + ((((ni_) * 2 + (kq >> 1)) ^ (r_ & 7)) * 16) + (kq & 1) * 8) = pk_; } while (0)
; __device__ void gemm1_phase(const Params& p, int l, int hb, unsigned char* smem) {
;     ...
;             for (int mi = 0; mi < 8; ++mi) {
; #pragma unroll
;                 for (int ni = 0; ni < 4; ++ni) {
;                     f32x4 v = acc[mi][ni];
;                     if (mode == 1) { v.x = siluf(v.x); v.y = siluf(v.y); v.z = siluf(v.z); v.w = siluf(v.w); }
;                     else if (mode == 2) { const f32x4 bb = *(const f32x4*)(bg + ni * 16); v.x = sigmf(v.x + bb.x); v.y = sigmf(v.y + bb.y); v.z = sigmf(v.z + bb.z); v.w = sigmf(v.w + bb.w); }
;                     G1_STG(mi, ni, v);
.LBB0_343:
	s_nop 0
	v_cvt_pk_bf16_f32 v134, v134, v135
	v_cvt_pk_bf16_f32 v135, v132, v133
	s_and_b64 vcc, exec, s[38:39]
	s_mov_b64 s[62:63], -1
	ds_write_b64 v138, v[134:135] offset:4096
	s_cbranch_vccnz .LBB0_347
	s_and_b64 vcc, exec, s[36:37]
	v_mov_b32_e32 v133, v79
	v_mov_b32_e32 v132, v78
	v_mov_b32_e32 v135, v77
	v_mov_b32_e32 v134, v76
	s_cbranch_vccnz .LBB0_346
	s_waitcnt vmcnt(0)
	v_mov_b32_e32 v132, v160
	v_mov_b32_e32 v133, v161
	v_mov_b32_e32 v134, v162
	v_mov_b32_e32 v135, v163
	v_add_f32_e32 v132, v76, v132
	v_add_f32_e32 v133, v77, v133
	v_add_f32_e32 v134, v78, v134
	v_add_f32_e32 v135, v79, v135
	v_mul_f32_e32 v132, 0xbfb8aa3b, v132
	v_mul_f32_e32 v133, 0xbfb8aa3b, v133
	v_mul_f32_e32 v134, 0xbfb8aa3b, v134
	v_mul_f32_e32 v135, 0xbfb8aa3b, v135
	v_exp_f32_e32 v132, v132
	v_exp_f32_e32 v133, v133
	v_exp_f32_e32 v134, v134
	v_exp_f32_e32 v135, v135
	v_add_f32_e32 v132, 1.0, v132
	v_add_f32_e32 v133, 1.0, v133
	v_add_f32_e32 v139, 1.0, v134
	v_add_f32_e32 v140, 1.0, v135
	v_rcp_f32_e32 v134, v132
	v_rcp_f32_e32 v135, v133
	v_rcp_f32_e32 v132, v139
	v_rcp_f32_e32 v133, v140

; __device__ __forceinline__ float siluf(float v) { return v * __builtin_amdgcn_rcpf(1.f + __builtin_amdgcn_exp2f(-1.4426950408889634f * v)); }
; __device__ __forceinline__ float sigmf(float v) { return __builtin_amdgcn_rcpf(1.f + __builtin_amdgcn_exp2f(-1.4426950408889634f * v)); }
; #define G1_STG(mi_, ni_, v_) do { const int r_ = (mi_) * 16 + idx; const f32x4 t_ = (v_); u32x2 pk_; pk_.x = pk2(t_.x, t_.y); pk_.y = pk2(t_.z, t_.w); \
;         *(u32x2*)(wl + r_ * 128 + ((((ni_) * 2 + (kq >> 1)) ^ (r_ & 7)) * 16) + (kq & 1) * 8) = pk_; } while (0)
; __device__ void gemm1_phase(const Params& p, int l, int hb, unsigned char* smem) {
;     ...
;             for (int mi = 0; mi < 8; ++mi) {
; #pragma unroll
;                 for (int ni = 0; ni < 4; ++ni) {
;                     f32x4 v = acc[mi][ni];
;                     if (mode == 1) { v.x = siluf(v.x); v.y = siluf(v.y); v.z = siluf(v.z); v.w = siluf(v.w); }
;                     else if (mode == 2) { const f32x4 bb = *(const f32x4*)(bg + ni * 16); v.x = sigmf(v.x + bb.x); v.y = sigmf(v.y + bb.y); v.z = sigmf(v.z + bb.z); v.w = sigmf(v.w + bb.w); }
;                     G1_STG(mi, ni, v);
.LBB0_349:
	s_nop 0
	v_cvt_pk_bf16_f32 v134, v134, v135
	v_cvt_pk_bf16_f32 v135, v132, v133
	s_and_b64 vcc, exec, s[38:39]
	s_mov_b64 s[62:63], -1
	ds_write_b64 v80, v[134:135] offset:6144
	s_cbranch_vccnz .LBB0_353
	s_and_b64 vcc, exec, s[36:37]
	v_mov_b32_e32 v133, v75
	v_mov_b32_e32 v132, v74
	v_mov_b32_e32 v135, v73
	v_mov_b32_e32 v134, v72
	s_cbranch_vccnz .LBB0_352
	s_waitcnt vmcnt(0)
	v_mov_b32_e32 v132, v164
	v_mov_b32_e32 v133, v165
	v_mov_b32_e32 v134, v166
	v_mov_b32_e32 v135, v167
	v_add_f32_e32 v132, v72, v132
	v_add_f32_e32 v133, v73, v133
	v_add_f32_e32 v134, v74, v134
	v_add_f32_e32 v135, v75, v135
	v_mul_f32_e32 v132, 0xbfb8aa3b, v132
	v_mul_f32_e32 v133, 0xbfb8aa3b, v133
	v_mul_f32_e32 v134, 0xbfb8aa3b, v134
	v_mul_f32_e32 v135, 0xbfb8aa3b, v135
	v_exp_f32_e32 v132, v132
	v_exp_f32_e32 v133, v133
	v_exp_f32_e32 v134, v134
	v_exp_f32_e32 v135, v135
	v_add_f32_e32 v132, 1.0, v132
	v_add_f32_e32 v133, 1.0, v133
	v_add_f32_e32 v139, 1.0, v134
	v_add_f32_e32 v140, 1.0, v135
	v_rcp_f32_e32 v134, v132
	v_rcp_f32_e32 v135, v133
	v_rcp_f32_e32 v132, v139
	v_rcp_f32_e32 v133, v140

; __device__ __forceinline__ float siluf(float v) { return v * __builtin_amdgcn_rcpf(1.f + __builtin_amdgcn_exp2f(-1.4426950408889634f * v)); }
; __device__ __forceinline__ float sigmf(float v) { return __builtin_amdgcn_rcpf(1.f + __builtin_amdgcn_exp2f(-1.4426950408889634f * v)); }
; #define G1_STG(mi_, ni_, v_) do { const int r_ = (mi_) * 16 + idx; const f32x4 t_ = (v_); u32x2 pk_; pk_.x = pk2(t_.x, t_.y); pk_.y = pk2(t_.z, t_.w); \
;         *(u32x2*)(wl + r_ * 128 + ((((ni_) * 2 + (kq >> 1)) ^ (r_ & 7)) * 16) + (kq & 1) * 8) = pk_; } while (0)
; __device__ void gemm1_phase(const Params& p, int l, int hb, unsigned char* smem) {
;     ...
;             for (int mi = 0; mi < 8; ++mi) {
; #pragma unroll
;                 for (int ni = 0; ni < 4; ++ni) {
;                     f32x4 v = acc[mi][ni];
;                     if (mode == 1) { v.x = siluf(v.x); v.y = siluf(v.y); v.z = siluf(v.z); v.w = siluf(v.w); }
;                     else if (mode == 2) { const f32x4 bb = *(const f32x4*)(bg + ni * 16); v.x = sigmf(v.x + bb.x); v.y = sigmf(v.y + bb.y); v.z = sigmf(v.z + bb.z); v.w = sigmf(v.w + bb.w); }
;                     G1_STG(mi, ni, v);
.LBB0_355:
	s_nop 0
	v_cvt_pk_bf16_f32 v134, v134, v135
	v_cvt_pk_bf16_f32 v135, v132, v133
	s_and_b64 vcc, exec, s[38:39]
	s_mov_b64 s[62:63], -1
	ds_write_b64 v136, v[134:135] offset:6144
	s_cbranch_vccnz .LBB0_359
	s_and_b64 vcc, exec, s[36:37]
	v_mov_b32_e32 v133, v71
	v_mov_b32_e32 v132, v70
	v_mov_b32_e32 v135, v69
	v_mov_b32_e32 v134, v68
	s_cbranch_vccnz .LBB0_358
	s_waitcnt vmcnt(0)
	v_mov_b32_e32 v132, v168
	v_mov_b32_e32 v133, v169
	v_mov_b32_e32 v134, v170
	v_mov_b32_e32 v135, v171
	v_add_f32_e32 v132, v68, v132
	v_add_f32_e32 v133, v69, v133
	v_add_f32_e32 v134, v70, v134
	v_add_f32_e32 v135, v71, v135
	v_mul_f32_e32 v132, 0xbfb8aa3b, v132
	v_mul_f32_e32 v133, 0xbfb8aa3b, v133
	v_mul_f32_e32 v134, 0xbfb8aa3b, v134
	v_mul_f32_e32 v135, 0xbfb8aa3b, v135
	v_exp_f32_e32 v132, v132
	v_exp_f32_e32 v133, v133
	v_exp_f32_e32 v134, v134
	v_exp_f32_e32 v135, v135
	v_add_f32_e32 v132, 1.0, v132
	v_add_f32_e32 v133, 1.0, v133
	v_add_f32_e32 v139, 1.0, v134
	v_add_f32_e32 v140, 1.0, v135
	v_rcp_f32_e32 v134, v132
	v_rcp_f32_e32 v135, v133
	v_rcp_f32_e32 v132, v139
	v_rcp_f32_e32 v133, v140

; __device__ __forceinline__ float siluf(float v) { return v * __builtin_amdgcn_rcpf(1.f + __builtin_amdgcn_exp2f(-1.4426950408889634f * v)); }
; __device__ __forceinline__ float sigmf(float v) { return __builtin_amdgcn_rcpf(1.f + __builtin_amdgcn_exp2f(-1.4426950408889634f * v)); }
; #define G1_STG(mi_, ni_, v_) do { const int r_ = (mi_) * 16 + idx; const f32x4 t_ = (v_); u32x2 pk_; pk_.x = pk2(t_.x, t_.y); pk_.y = pk2(t_.z, t_.w); \
;         *(u32x2*)(wl + r_ * 128 + ((((ni_) * 2 + (kq >> 1)) ^ (r_ & 7)) * 16) + (kq & 1) * 8) = pk_; } while (0)
; __device__ void gemm1_phase(const Params& p, int l, int hb, unsigned char* smem) {
;     ...
;             for (int mi = 0; mi < 8; ++mi) {
; #pragma unroll
;                 for (int ni = 0; ni < 4; ++ni) {
;                     f32x4 v = acc[mi][ni];
;                     if (mode == 1) { v.x = siluf(v.x); v.y = siluf(v.y); v.z = siluf(v.z); v.w = siluf(v.w); }
;                     else if (mode == 2) { const f32x4 bb = *(const f32x4*)(bg + ni * 16); v.x = sigmf(v.x + bb.x); v.y = sigmf(v.y + bb.y); v.z = sigmf(v.z + bb.z); v.w = sigmf(v.w + bb.w); }
;                     G1_STG(mi, ni, v);
.LBB0_361:
	s_nop 0
	v_cvt_pk_bf16_f32 v134, v134, v135
	v_cvt_pk_bf16_f32 v135, v132, v133
	s_and_b64 vcc, exec, s[38:39]
	s_mov_b64 s[62:63], -1
	ds_write_b64 v137, v[134:135] offset:6144
	s_cbranch_vccnz .LBB0_365
	s_and_b64 vcc, exec, s[36:37]
	v_mov_b32_e32 v133, v67
	v_mov_b32_e32 v132, v66
	v_mov_b32_e32 v135, v65
	v_mov_b32_e32 v134, v64
	s_cbranch_vccnz .LBB0_364
	s_waitcnt vmcnt(0)
	v_mov_b32_e32 v132, v172
	v_mov_b32_e32 v133, v173
	v_mov_b32_e32 v134, v174
	v_mov_b32_e32 v135, v175
	v_add_f32_e32 v132, v64, v132
	v_add_f32_e32 v133, v65, v133
	v_add_f32_e32 v134, v66, v134
	v_add_f32_e32 v135, v67, v135
	v_mul_f32_e32 v132, 0xbfb8aa3b, v132
	v_mul_f32_e32 v133, 0xbfb8aa3b, v133
	v_mul_f32_e32 v134, 0xbfb8aa3b, v134
	v_mul_f32_e32 v135, 0xbfb8aa3b, v135
	v_exp_f32_e32 v132, v132
	v_exp_f32_e32 v133, v133
	v_exp_f32_e32 v134, v134
	v_exp_f32_e32 v135, v135
	v_add_f32_e32 v132, 1.0, v132
	v_add_f32_e32 v133, 1.0, v133
	v_add_f32_e32 v139, 1.0, v134
	v_add_f32_e32 v140, 1.0, v135
	v_rcp_f32_e32 v134, v132
	v_rcp_f32_e32 v135, v133
	v_rcp_f32_e32 v132, v139
	v_rcp_f32_e32 v133, v140

; __device__ __forceinline__ float siluf(float v) { return v * __builtin_amdgcn_rcpf(1.f + __builtin_amdgcn_exp2f(-1.4426950408889634f * v)); }
; __device__ __forceinline__ float sigmf(float v) { return __builtin_amdgcn_rcpf(1.f + __builtin_amdgcn_exp2f(-1.4426950408889634f * v)); }
; #define G1_STG(mi_, ni_, v_) do { const int r_ = (mi_) * 16 + idx; const f32x4 t_ = (v_); u32x2 pk_; pk_.x = pk2(t_.x, t_.y); pk_.y = pk2(t_.z, t_.w); \
;         *(u32x2*)(wl + r_ * 128 + ((((ni_) * 2 + (kq >> 1)) ^ (r_ & 7)) * 16) + (kq & 1) * 8) = pk_; } while (0)
; __device__ void gemm1_phase(const Params& p, int l, int hb, unsigned char* smem) {
;     ...
;             for (int mi = 0; mi < 8; ++mi) {
; #pragma unroll
;                 for (int ni = 0; ni < 4; ++ni) {
;                     f32x4 v = acc[mi][ni];
;                     if (mode == 1) { v.x = siluf(v.x); v.y = siluf(v.y); v.z = siluf(v.z); v.w = siluf(v.w); }
;                     else if (mode == 2) { const f32x4 bb = *(const f32x4*)(bg + ni * 16); v.x = sigmf(v.x + bb.x); v.y = sigmf(v.y + bb.y); v.z = sigmf(v.z + bb.z); v.w = sigmf(v.w + bb.w); }
;                     G1_STG(mi, ni, v);
.LBB0_367:
	s_nop 0
	v_cvt_pk_bf16_f32 v134, v134, v135
	v_cvt_pk_bf16_f32 v135, v132, v133
	s_and_b64 vcc, exec, s[38:39]
	s_mov_b64 s[62:63], -1
	ds_write_b64 v138, v[134:135] offset:6144
	s_cbranch_vccnz .LBB0_371
	s_and_b64 vcc, exec, s[36:37]
	v_mov_b32_e32 v133, v63
	v_mov_b32_e32 v132, v62
	v_mov_b32_e32 v135, v61
	v_mov_b32_e32 v134, v60
	s_cbranch_vccnz .LBB0_370
	s_waitcnt vmcnt(0)
	v_mov_b32_e32 v132, v160
	v_mov_b32_e32 v133, v161
	v_mov_b32_e32 v134, v162
	v_mov_b32_e32 v135, v163
	v_add_f32_e32 v132, v60, v132
	v_add_f32_e32 v133, v61, v133
	v_add_f32_e32 v134, v62, v134
	v_add_f32_e32 v135, v63, v135
	v_mul_f32_e32 v132, 0xbfb8aa3b, v132
	v_mul_f32_e32 v133, 0xbfb8aa3b, v133
	v_mul_f32_e32 v134, 0xbfb8aa3b, v134
	v_mul_f32_e32 v135, 0xbfb8aa3b, v135
	v_exp_f32_e32 v132, v132
	v_exp_f32_e32 v133, v133
	v_exp_f32_e32 v134, v134
	v_exp_f32_e32 v135, v135
	v_add_f32_e32 v132, 1.0, v132
	v_add_f32_e32 v133, 1.0, v133
	v_add_f32_e32 v139, 1.0, v134
	v_add_f32_e32 v140, 1.0, v135
	v_rcp_f32_e32 v134, v132
	v_rcp_f32_e32 v135, v133
	v_rcp_f32_e32 v132, v139
	v_rcp_f32_e32 v133, v140

; __device__ __forceinline__ float siluf(float v) { return v * __builtin_amdgcn_rcpf(1.f + __builtin_amdgcn_exp2f(-1.4426950408889634f * v)); }
; __device__ __forceinline__ float sigmf(float v) { return __builtin_amdgcn_rcpf(1.f + __builtin_amdgcn_exp2f(-1.4426950408889634f * v)); }
; #define G1_STG(mi_, ni_, v_) do { const int r_ = (mi_) * 16 + idx; const f32x4 t_ = (v_); u32x2 pk_; pk_.x = pk2(t_.x, t_.y); pk_.y = pk2(t_.z, t_.w); \
;         *(u32x2*)(wl + r_ * 128 + ((((ni_) * 2 + (kq >> 1)) ^ (r_ & 7)) * 16) + (kq & 1) * 8) = pk_; } while (0)
; __device__ void gemm1_phase(const Params& p, int l, int hb, unsigned char* smem) {
;     ...
;             for (int mi = 0; mi < 8; ++mi) {
; #pragma unroll
;                 for (int ni = 0; ni < 4; ++ni) {
;                     f32x4 v = acc[mi][ni];
;                     if (mode == 1) { v.x = siluf(v.x); v.y = siluf(v.y); v.z = siluf(v.z); v.w = siluf(v.w); }
;                     else if (mode == 2) { const f32x4 bb = *(const f32x4*)(bg + ni * 16); v.x = sigmf(v.x + bb.x); v.y = sigmf(v.y + bb.y); v.z = sigmf(v.z + bb.z); v.w = sigmf(v.w + bb.w); }
;                     G1_STG(mi, ni, v);
.LBB0_373:
	s_nop 0
	v_cvt_pk_bf16_f32 v134, v134, v135
	v_cvt_pk_bf16_f32 v135, v132, v133
	s_and_b64 vcc, exec, s[38:39]
	s_mov_b64 s[62:63], -1
	ds_write_b64 v80, v[134:135] offset:8192
	s_cbranch_vccnz .LBB0_377
	s_and_b64 vcc, exec, s[36:37]
	v_mov_b32_e32 v133, v59
	v_mov_b32_e32 v132, v58
	v_mov_b32_e32 v135, v57
	v_mov_b32_e32 v134, v56
	s_cbranch_vccnz .LBB0_376
	s_waitcnt vmcnt(0)
	v_mov_b32_e32 v132, v164
	v_mov_b32_e32 v133, v165
	v_mov_b32_e32 v134, v166
	v_mov_b32_e32 v135, v167
	v_add_f32_e32 v132, v56, v132
	v_add_f32_e32 v133, v57, v133
	v_add_f32_e32 v134, v58, v134
	v_add_f32_e32 v135, v59, v135
	v_mul_f32_e32 v132, 0xbfb8aa3b, v132
	v_mul_f32_e32 v133, 0xbfb8aa3b, v133
	v_mul_f32_e32 v134, 0xbfb8aa3b, v134
	v_mul_f32_e32 v135, 0xbfb8aa3b, v135
	v_exp_f32_e32 v132, v132
	v_exp_f32_e32 v133, v133
	v_exp_f32_e32 v134, v134
	v_exp_f32_e32 v135, v135
	v_add_f32_e32 v132, 1.0, v132
	v_add_f32_e32 v133, 1.0, v133
	v_add_f32_e32 v139, 1.0, v134
	v_add_f32_e32 v140, 1.0, v135
	v_rcp_f32_e32 v134, v132
	v_rcp_f32_e32 v135, v133
	v_rcp_f32_e32 v132, v139
	v_rcp_f32_e32 v133, v140

; __device__ __forceinline__ float siluf(float v) { return v * __builtin_amdgcn_rcpf(1.f + __builtin_amdgcn_exp2f(-1.4426950408889634f * v)); }
; __device__ __forceinline__ float sigmf(float v) { return __builtin_amdgcn_rcpf(1.f + __builtin_amdgcn_exp2f(-1.4426950408889634f * v)); }
; #define G1_STG(mi_, ni_, v_) do { const int r_ = (mi_) * 16 + idx; const f32x4 t_ = (v_); u32x2 pk_; pk_.x = pk2(t_.x, t_.y); pk_.y = pk2(t_.z, t_.w); \
;         *(u32x2*)(wl + r_ * 128 + ((((ni_) * 2 + (kq >> 1)) ^ (r_ & 7)) * 16) + (kq & 1) * 8) = pk_; } while (0)
; __device__ void gemm1_phase(const Params& p, int l, int hb, unsigned char* smem) {
;     ...
;             for (int mi = 0; mi < 8; ++mi) {
; #pragma unroll
;                 for (int ni = 0; ni < 4; ++ni) {
;                     f32x4 v = acc[mi][ni];
;                     if (mode == 1) { v.x = siluf(v.x); v.y = siluf(v.y); v.z = siluf(v.z); v.w = siluf(v.w); }
;                     else if (mode == 2) { const f32x4 bb = *(const f32x4*)(bg + ni * 16); v.x = sigmf(v.x + bb.x); v.y = sigmf(v.y + bb.y); v.z = sigmf(v.z + bb.z); v.w = sigmf(v.w + bb.w); }
;                     G1_STG(mi, ni, v);
.LBB0_379:
	s_nop 0
	v_cvt_pk_bf16_f32 v134, v134, v135
	v_cvt_pk_bf16_f32 v135, v132, v133
	s_and_b64 vcc, exec, s[38:39]
	s_mov_b64 s[62:63], -1
	ds_write_b64 v136, v[134:135] offset:8192
	s_cbranch_vccnz .LBB0_383
	s_and_b64 vcc, exec, s[36:37]
	v_mov_b32_e32 v133, v55
	v_mov_b32_e32 v132, v54
	v_mov_b32_e32 v135, v53
	v_mov_b32_e32 v134, v52
	s_cbranch_vccnz .LBB0_382
	s_waitcnt vmcnt(0)
	v_mov_b32_e32 v132, v168
	v_mov_b32_e32 v133, v169
	v_mov_b32_e32 v134, v170
	v_mov_b32_e32 v135, v171
	v_add_f32_e32 v132, v52, v132
	v_add_f32_e32 v133, v53, v133
	v_add_f32_e32 v134, v54, v134
	v_add_f32_e32 v135, v55, v135
	v_mul_f32_e32 v132, 0xbfb8aa3b, v132
	v_mul_f32_e32 v133, 0xbfb8aa3b, v133
	v_mul_f32_e32 v134, 0xbfb8aa3b, v134
	v_mul_f32_e32 v135, 0xbfb8aa3b, v135
	v_exp_f32_e32 v132, v132
	v_exp_f32_e32 v133, v133
	v_exp_f32_e32 v134, v134
	v_exp_f32_e32 v135, v135
	v_add_f32_e32 v132, 1.0, v132
	v_add_f32_e32 v133, 1.0, v133
	v_add_f32_e32 v139, 1.0, v134
	v_add_f32_e32 v140, 1.0, v135
	v_rcp_f32_e32 v134, v132
	v_rcp_f32_e32 v135, v133
	v_rcp_f32_e32 v132, v139
	v_rcp_f32_e32 v133, v140

; __device__ __forceinline__ float siluf(float v) { return v * __builtin_amdgcn_rcpf(1.f + __builtin_amdgcn_exp2f(-1.4426950408889634f * v)); }
; __device__ __forceinline__ float sigmf(float v) { return __builtin_amdgcn_rcpf(1.f + __builtin_amdgcn_exp2f(-1.4426950408889634f * v)); }
; #define G1_STG(mi_, ni_, v_) do { const int r_ = (mi_) * 16 + idx; const f32x4 t_ = (v_); u32x2 pk_; pk_.x = pk2(t_.x, t_.y); pk_.y = pk2(t_.z, t_.w); \
;         *(u32x2*)(wl + r_ * 128 + ((((ni_) * 2 + (kq >> 1)) ^ (r_ & 7)) * 16) + (kq & 1) * 8) = pk_; } while (0)
; __device__ void gemm1_phase(const Params& p, int l, int hb, unsigned char* smem) {
;     ...
;             for (int mi = 0; mi < 8; ++mi) {
; #pragma unroll
;                 for (int ni = 0; ni < 4; ++ni) {
;                     f32x4 v = acc[mi][ni];
;                     if (mode == 1) { v.x = siluf(v.x); v.y = siluf(v.y); v.z = siluf(v.z); v.w = siluf(v.w); }
;                     else if (mode == 2) { const f32x4 bb = *(const f32x4*)(bg + ni * 16); v.x = sigmf(v.x + bb.x); v.y = sigmf(v.y + bb.y); v.z = sigmf(v.z + bb.z); v.w = sigmf(v.w + bb.w); }
;                     G1_STG(mi, ni, v);
.LBB0_385:
	s_nop 0
	v_cvt_pk_bf16_f32 v134, v134, v135
	v_cvt_pk_bf16_f32 v135, v132, v133
	s_and_b64 vcc, exec, s[38:39]
	s_mov_b64 s[62:63], -1
	ds_write_b64 v137, v[134:135] offset:8192
	s_cbranch_vccnz .LBB0_389
	s_and_b64 vcc, exec, s[36:37]
	v_mov_b32_e32 v133, v51
	v_mov_b32_e32 v132, v50
	v_mov_b32_e32 v135, v49
	v_mov_b32_e32 v134, v48
	s_cbranch_vccnz .LBB0_388
	s_waitcnt vmcnt(0)
	v_mov_b32_e32 v132, v172
	v_mov_b32_e32 v133, v173
	v_mov_b32_e32 v134, v174
	v_mov_b32_e32 v135, v175
	v_add_f32_e32 v132, v48, v132
	v_add_f32_e32 v133, v49, v133
	v_add_f32_e32 v134, v50, v134
	v_add_f32_e32 v135, v51, v135
	v_mul_f32_e32 v132, 0xbfb8aa3b, v132
	v_mul_f32_e32 v133, 0xbfb8aa3b, v133
	v_mul_f32_e32 v134, 0xbfb8aa3b, v134
	v_mul_f32_e32 v135, 0xbfb8aa3b, v135
	v_exp_f32_e32 v132, v132
	v_exp_f32_e32 v133, v133
	v_exp_f32_e32 v134, v134
	v_exp_f32_e32 v135, v135
	v_add_f32_e32 v132, 1.0, v132
	v_add_f32_e32 v133, 1.0, v133
	v_add_f32_e32 v139, 1.0, v134
	v_add_f32_e32 v140, 1.0, v135
	v_rcp_f32_e32 v134, v132
	v_rcp_f32_e32 v135, v133
	v_rcp_f32_e32 v132, v139
	v_rcp_f32_e32 v133, v140

; __device__ __forceinline__ float siluf(float v) { return v * __builtin_amdgcn_rcpf(1.f + __builtin_amdgcn_exp2f(-1.4426950408889634f * v)); }
; __device__ __forceinline__ float sigmf(float v) { return __builtin_amdgcn_rcpf(1.f + __builtin_amdgcn_exp2f(-1.4426950408889634f * v)); }
; #define G1_STG(mi_, ni_, v_) do { const int r_ = (mi_) * 16 + idx; const f32x4 t_ = (v_); u32x2 pk_; pk_.x = pk2(t_.x, t_.y); pk_.y = pk2(t_.z, t_.w); \
;         *(u32x2*)(wl + r_ * 128 + ((((ni_) * 2 + (kq >> 1)) ^ (r_ & 7)) * 16) + (kq & 1) * 8) = pk_; } while (0)
; __device__ void gemm1_phase(const Params& p, int l, int hb, unsigned char* smem) {
;     ...
;             for (int mi = 0; mi < 8; ++mi) {
; #pragma unroll
;                 for (int ni = 0; ni < 4; ++ni) {
;                     f32x4 v = acc[mi][ni];
;                     if (mode == 1) { v.x = siluf(v.x); v.y = siluf(v.y); v.z = siluf(v.z); v.w = siluf(v.w); }
;                     else if (mode == 2) { const f32x4 bb = *(const f32x4*)(bg + ni * 16); v.x = sigmf(v.x + bb.x); v.y = sigmf(v.y + bb.y); v.z = sigmf(v.z + bb.z); v.w = sigmf(v.w + bb.w); }
;                     G1_STG(mi, ni, v);
.LBB0_391:
	s_nop 0
	v_cvt_pk_bf16_f32 v134, v134, v135
	v_cvt_pk_bf16_f32 v135, v132, v133
	s_and_b64 vcc, exec, s[38:39]
	s_mov_b64 s[62:63], -1
	ds_write_b64 v138, v[134:135] offset:8192
	s_cbranch_vccnz .LBB0_395
	s_and_b64 vcc, exec, s[36:37]
	v_mov_b32_e32 v133, v47
	v_mov_b32_e32 v132, v46
	v_mov_b32_e32 v135, v45
	v_mov_b32_e32 v134, v44
	s_cbranch_vccnz .LBB0_394
	s_waitcnt vmcnt(0)
	v_mov_b32_e32 v132, v160
	v_mov_b32_e32 v133, v161
	v_mov_b32_e32 v134, v162
	v_mov_b32_e32 v135, v163
	v_add_f32_e32 v132, v44, v132
	v_add_f32_e32 v133, v45, v133
	v_add_f32_e32 v134, v46, v134
	v_add_f32_e32 v135, v47, v135
	v_mul_f32_e32 v132, 0xbfb8aa3b, v132
	v_mul_f32_e32 v133, 0xbfb8aa3b, v133
	v_mul_f32_e32 v134, 0xbfb8aa3b, v134
	v_mul_f32_e32 v135, 0xbfb8aa3b, v135
	v_exp_f32_e32 v132, v132
	v_exp_f32_e32 v133, v133
	v_exp_f32_e32 v134, v134
	v_exp_f32_e32 v135, v135
	v_add_f32_e32 v132, 1.0, v132
	v_add_f32_e32 v133, 1.0, v133
	v_add_f32_e32 v139, 1.0, v134
	v_add_f32_e32 v140, 1.0, v135
	v_rcp_f32_e32 v134, v132
	v_rcp_f32_e32 v135, v133
	v_rcp_f32_e32 v132, v139
	v_rcp_f32_e32 v133, v140

; __device__ __forceinline__ float siluf(float v) { return v * __builtin_amdgcn_rcpf(1.f + __builtin_amdgcn_exp2f(-1.4426950408889634f * v)); }
; __device__ __forceinline__ float sigmf(float v) { return __builtin_amdgcn_rcpf(1.f + __builtin_amdgcn_exp2f(-1.4426950408889634f * v)); }
; #define G1_STG(mi_, ni_, v_) do { const int r_ = (mi_) * 16 + idx; const f32x4 t_ = (v_); u32x2 pk_; pk_.x = pk2(t_.x, t_.y); pk_.y = pk2(t_.z, t_.w); \
;         *(u32x2*)(wl + r_ * 128 + ((((ni_) * 2 + (kq >> 1)) ^ (r_ & 7)) * 16) + (kq & 1) * 8) = pk_; } while (0)
; __device__ void gemm1_phase(const Params& p, int l, int hb, unsigned char* smem) {
;     ...
;             for (int mi = 0; mi < 8; ++mi) {
; #pragma unroll
;                 for (int ni = 0; ni < 4; ++ni) {
;                     f32x4 v = acc[mi][ni];
;                     if (mode == 1) { v.x = siluf(v.x); v.y = siluf(v.y); v.z = siluf(v.z); v.w = siluf(v.w); }
;                     else if (mode == 2) { const f32x4 bb = *(const f32x4*)(bg + ni * 16); v.x = sigmf(v.x + bb.x); v.y = sigmf(v.y + bb.y); v.z = sigmf(v.z + bb.z); v.w = sigmf(v.w + bb.w); }
;                     G1_STG(mi, ni, v);
.LBB0_397:
	s_nop 0
	v_cvt_pk_bf16_f32 v134, v134, v135
	v_cvt_pk_bf16_f32 v135, v132, v133
	s_and_b64 vcc, exec, s[38:39]
	s_mov_b64 s[62:63], -1
	ds_write_b64 v80, v[134:135] offset:10240
	s_cbranch_vccnz .LBB0_401
	s_and_b64 vcc, exec, s[36:37]
	v_mov_b32_e32 v133, v43
	v_mov_b32_e32 v132, v42
	v_mov_b32_e32 v135, v41
	v_mov_b32_e32 v134, v40
	s_cbranch_vccnz .LBB0_400
	s_waitcnt vmcnt(0)
	v_mov_b32_e32 v132, v164
	v_mov_b32_e32 v133, v165
	v_mov_b32_e32 v134, v166
	v_mov_b32_e32 v135, v167
	v_add_f32_e32 v132, v40, v132
	v_add_f32_e32 v133, v41, v133
	v_add_f32_e32 v134, v42, v134
	v_add_f32_e32 v135, v43, v135
	v_mul_f32_e32 v132, 0xbfb8aa3b, v132
	v_mul_f32_e32 v133, 0xbfb8aa3b, v133
	v_mul_f32_e32 v134, 0xbfb8aa3b, v134
	v_mul_f32_e32 v135, 0xbfb8aa3b, v135
	v_exp_f32_e32 v132, v132
	v_exp_f32_e32 v133, v133
	v_exp_f32_e32 v134, v134
	v_exp_f32_e32 v135, v135
	v_add_f32_e32 v132, 1.0, v132
	v_add_f32_e32 v133, 1.0, v133
	v_add_f32_e32 v139, 1.0, v134
	v_add_f32_e32 v140, 1.0, v135
	v_rcp_f32_e32 v134, v132
	v_rcp_f32_e32 v135, v133
	v_rcp_f32_e32 v132, v139
	v_rcp_f32_e32 v133, v140

; __device__ __forceinline__ float siluf(float v) { return v * __builtin_amdgcn_rcpf(1.f + __builtin_amdgcn_exp2f(-1.4426950408889634f * v)); }
; __device__ __forceinline__ float sigmf(float v) { return __builtin_amdgcn_rcpf(1.f + __builtin_amdgcn_exp2f(-1.4426950408889634f * v)); }
; #define G1_STG(mi_, ni_, v_) do { const int r_ = (mi_) * 16 + idx; const f32x4 t_ = (v_); u32x2 pk_; pk_.x = pk2(t_.x, t_.y); pk_.y = pk2(t_.z, t_.w); \
;         *(u32x2*)(wl + r_ * 128 + ((((ni_) * 2 + (kq >> 1)) ^ (r_ & 7)) * 16) + (kq & 1) * 8) = pk_; } while (0)
; __device__ void gemm1_phase(const Params& p, int l, int hb, unsigned char* smem) {
;     ...
;             for (int mi = 0; mi < 8; ++mi) {
; #pragma unroll
;                 for (int ni = 0; ni < 4; ++ni) {
;                     f32x4 v = acc[mi][ni];
;                     if (mode == 1) { v.x = siluf(v.x); v.y = siluf(v.y); v.z = siluf(v.z); v.w = siluf(v.w); }
;                     else if (mode == 2) { const f32x4 bb = *(const f32x4*)(bg + ni * 16); v.x = sigmf(v.x + bb.x); v.y = sigmf(v.y + bb.y); v.z = sigmf(v.z + bb.z); v.w = sigmf(v.w + bb.w); }
;                     G1_STG(mi, ni, v);
.LBB0_403:
	s_nop 0
	v_cvt_pk_bf16_f32 v134, v134, v135
	v_cvt_pk_bf16_f32 v135, v132, v133
	s_and_b64 vcc, exec, s[38:39]
	s_mov_b64 s[62:63], -1
	ds_write_b64 v136, v[134:135] offset:10240
	s_cbranch_vccnz .LBB0_407
	s_and_b64 vcc, exec, s[36:37]
	v_mov_b32_e32 v133, v39
	v_mov_b32_e32 v132, v38
	v_mov_b32_e32 v135, v37
	v_mov_b32_e32 v134, v36
	s_cbranch_vccnz .LBB0_406
	s_waitcnt vmcnt(0)
	v_mov_b32_e32 v132, v168
	v_mov_b32_e32 v133, v169
	v_mov_b32_e32 v134, v170
	v_mov_b32_e32 v135, v171
	v_add_f32_e32 v132, v36, v132
	v_add_f32_e32 v133, v37, v133
	v_add_f32_e32 v134, v38, v134
	v_add_f32_e32 v135, v39, v135
	v_mul_f32_e32 v132, 0xbfb8aa3b, v132
	v_mul_f32_e32 v133, 0xbfb8aa3b, v133
	v_mul_f32_e32 v134, 0xbfb8aa3b, v134
	v_mul_f32_e32 v135, 0xbfb8aa3b, v135
	v_exp_f32_e32 v132, v132
	v_exp_f32_e32 v133, v133
	v_exp_f32_e32 v134, v134
	v_exp_f32_e32 v135, v135
	v_add_f32_e32 v132, 1.0, v132
	v_add_f32_e32 v133, 1.0, v133
	v_add_f32_e32 v139, 1.0, v134
	v_add_f32_e32 v140, 1.0, v135
	v_rcp_f32_e32 v134, v132
	v_rcp_f32_e32 v135, v133
	v_rcp_f32_e32 v132, v139
	v_rcp_f32_e32 v133, v140

; __device__ __forceinline__ float siluf(float v) { return v * __builtin_amdgcn_rcpf(1.f + __builtin_amdgcn_exp2f(-1.4426950408889634f * v)); }
; __device__ __forceinline__ float sigmf(float v) { return __builtin_amdgcn_rcpf(1.f + __builtin_amdgcn_exp2f(-1.4426950408889634f * v)); }
; #define G1_STG(mi_, ni_, v_) do { const int r_ = (mi_) * 16 + idx; const f32x4 t_ = (v_); u32x2 pk_; pk_.x = pk2(t_.x, t_.y); pk_.y = pk2(t_.z, t_.w); \
;         *(u32x2*)(wl + r_ * 128 + ((((ni_) * 2 + (kq >> 1)) ^ (r_ & 7)) * 16) + (kq & 1) * 8) = pk_; } while (0)
; __device__ void gemm1_phase(const Params& p, int l, int hb, unsigned char* smem) {
;     ...
;             for (int mi = 0; mi < 8; ++mi) {
; #pragma unroll
;                 for (int ni = 0; ni < 4; ++ni) {
;                     f32x4 v = acc[mi][ni];
;                     if (mode == 1) { v.x = siluf(v.x); v.y = siluf(v.y); v.z = siluf(v.z); v.w = siluf(v.w); }
;                     else if (mode == 2) { const f32x4 bb = *(const f32x4*)(bg + ni * 16); v.x = sigmf(v.x + bb.x); v.y = sigmf(v.y + bb.y); v.z = sigmf(v.z + bb.z); v.w = sigmf(v.w + bb.w); }
;                     G1_STG(mi, ni, v);
.LBB0_409:
	s_nop 0
	v_cvt_pk_bf16_f32 v134, v134, v135
	v_cvt_pk_bf16_f32 v135, v132, v133
	s_and_b64 vcc, exec, s[38:39]
	s_mov_b64 s[62:63], -1
	ds_write_b64 v137, v[134:135] offset:10240
	s_cbranch_vccnz .LBB0_413
	s_and_b64 vcc, exec, s[36:37]
	v_mov_b32_e32 v133, v35
	v_mov_b32_e32 v132, v34
	v_mov_b32_e32 v135, v33
	v_mov_b32_e32 v134, v32
	s_cbranch_vccnz .LBB0_412
	s_waitcnt vmcnt(0)
	v_mov_b32_e32 v132, v172
	v_mov_b32_e32 v133, v173
	v_mov_b32_e32 v134, v174
	v_mov_b32_e32 v135, v175
	v_add_f32_e32 v132, v32, v132
	v_add_f32_e32 v133, v33, v133
	v_add_f32_e32 v134, v34, v134
	v_add_f32_e32 v135, v35, v135
	v_mul_f32_e32 v132, 0xbfb8aa3b, v132
	v_mul_f32_e32 v133, 0xbfb8aa3b, v133
	v_mul_f32_e32 v134, 0xbfb8aa3b, v134
	v_mul_f32_e32 v135, 0xbfb8aa3b, v135
	v_exp_f32_e32 v132, v132
	v_exp_f32_e32 v133, v133
	v_exp_f32_e32 v134, v134
	v_exp_f32_e32 v135, v135
	v_add_f32_e32 v132, 1.0, v132
	v_add_f32_e32 v133, 1.0, v133
	v_add_f32_e32 v139, 1.0, v134
	v_add_f32_e32 v140, 1.0, v135
	v_rcp_f32_e32 v134, v132
	v_rcp_f32_e32 v135, v133
	v_rcp_f32_e32 v132, v139
	v_rcp_f32_e32 v133, v140

; __device__ __forceinline__ float siluf(float v) { return v * __builtin_amdgcn_rcpf(1.f + __builtin_amdgcn_exp2f(-1.4426950408889634f * v)); }
; __device__ __forceinline__ float sigmf(float v) { return __builtin_amdgcn_rcpf(1.f + __builtin_amdgcn_exp2f(-1.4426950408889634f * v)); }
; #define G1_STG(mi_, ni_, v_) do { const int r_ = (mi_) * 16 + idx; const f32x4 t_ = (v_); u32x2 pk_; pk_.x = pk2(t_.x, t_.y); pk_.y = pk2(t_.z, t_.w); \
;         *(u32x2*)(wl + r_ * 128 + ((((ni_) * 2 + (kq >> 1)) ^ (r_ & 7)) * 16) + (kq & 1) * 8) = pk_; } while (0)
; __device__ void gemm1_phase(const Params& p, int l, int hb, unsigned char* smem) {
;     ...
;             for (int mi = 0; mi < 8; ++mi) {
; #pragma unroll
;                 for (int ni = 0; ni < 4; ++ni) {
;                     f32x4 v = acc[mi][ni];
;                     if (mode == 1) { v.x = siluf(v.x); v.y = siluf(v.y); v.z = siluf(v.z); v.w = siluf(v.w); }
;                     else if (mode == 2) { const f32x4 bb = *(const f32x4*)(bg + ni * 16); v.x = sigmf(v.x + bb.x); v.y = sigmf(v.y + bb.y); v.z = sigmf(v.z + bb.z); v.w = sigmf(v.w + bb.w); }
;                     G1_STG(mi, ni, v);
.LBB0_415:
	s_nop 0
	v_cvt_pk_bf16_f32 v134, v134, v135
	v_cvt_pk_bf16_f32 v135, v132, v133
	s_and_b64 vcc, exec, s[38:39]
	s_mov_b64 s[62:63], -1
	ds_write_b64 v138, v[134:135] offset:10240
	s_cbranch_vccnz .LBB0_419
	s_and_b64 vcc, exec, s[36:37]
	v_mov_b32_e32 v133, v31
	v_mov_b32_e32 v132, v30
	v_mov_b32_e32 v135, v29
	v_mov_b32_e32 v134, v28
	s_cbranch_vccnz .LBB0_418
	s_waitcnt vmcnt(0)
	v_mov_b32_e32 v132, v160
	v_mov_b32_e32 v133, v161
	v_mov_b32_e32 v134, v162
	v_mov_b32_e32 v135, v163
	v_add_f32_e32 v132, v28, v132
	v_add_f32_e32 v133, v29, v133
	v_add_f32_e32 v134, v30, v134
	v_add_f32_e32 v135, v31, v135
	v_mul_f32_e32 v132, 0xbfb8aa3b, v132
	v_mul_f32_e32 v133, 0xbfb8aa3b, v133
	v_mul_f32_e32 v134, 0xbfb8aa3b, v134
	v_mul_f32_e32 v135, 0xbfb8aa3b, v135
	v_exp_f32_e32 v132, v132
	v_exp_f32_e32 v133, v133
	v_exp_f32_e32 v134, v134
	v_exp_f32_e32 v135, v135
	v_add_f32_e32 v132, 1.0, v132
	v_add_f32_e32 v133, 1.0, v133
	v_add_f32_e32 v139, 1.0, v134
	v_add_f32_e32 v140, 1.0, v135
	v_rcp_f32_e32 v134, v132
	v_rcp_f32_e32 v135, v133
	v_rcp_f32_e32 v132, v139
	v_rcp_f32_e32 v133, v140

; __device__ __forceinline__ float siluf(float v) { return v * __builtin_amdgcn_rcpf(1.f + __builtin_amdgcn_exp2f(-1.4426950408889634f * v)); }
; __device__ __forceinline__ float sigmf(float v) { return __builtin_amdgcn_rcpf(1.f + __builtin_amdgcn_exp2f(-1.4426950408889634f * v)); }
; #define G1_STG(mi_, ni_, v_) do { const int r_ = (mi_) * 16 + idx; const f32x4 t_ = (v_); u32x2 pk_; pk_.x = pk2(t_.x, t_.y); pk_.y = pk2(t_.z, t_.w); \
;         *(u32x2*)(wl + r_ * 128 + ((((ni_) * 2 + (kq >> 1)) ^ (r_ & 7)) * 16) + (kq & 1) * 8) = pk_; } while (0)
; __device__ void gemm1_phase(const Params& p, int l, int hb, unsigned char* smem) {
;     ...
;             for (int mi = 0; mi < 8; ++mi) {
; #pragma unroll
;                 for (int ni = 0; ni < 4; ++ni) {
;                     f32x4 v = acc[mi][ni];
;                     if (mode == 1) { v.x = siluf(v.x); v.y = siluf(v.y); v.z = siluf(v.z); v.w = siluf(v.w); }
;                     else if (mode == 2) { const f32x4 bb = *(const f32x4*)(bg + ni * 16); v.x = sigmf(v.x + bb.x); v.y = sigmf(v.y + bb.y); v.z = sigmf(v.z + bb.z); v.w = sigmf(v.w + bb.w); }
;                     G1_STG(mi, ni, v);
.LBB0_421:
	s_nop 0
	v_cvt_pk_bf16_f32 v134, v134, v135
	v_cvt_pk_bf16_f32 v135, v132, v133
	s_and_b64 vcc, exec, s[38:39]
	s_mov_b64 s[62:63], -1
	ds_write_b64 v80, v[134:135] offset:12288
	s_cbranch_vccnz .LBB0_425
	s_and_b64 vcc, exec, s[36:37]
	v_mov_b32_e32 v133, v27
	v_mov_b32_e32 v132, v26
	v_mov_b32_e32 v135, v25
	v_mov_b32_e32 v134, v24
	s_cbranch_vccnz .LBB0_424
	s_waitcnt vmcnt(0)
	v_mov_b32_e32 v132, v164
	v_mov_b32_e32 v133, v165
	v_mov_b32_e32 v134, v166
	v_mov_b32_e32 v135, v167
	v_add_f32_e32 v132, v24, v132
	v_add_f32_e32 v133, v25, v133
	v_add_f32_e32 v134, v26, v134
	v_add_f32_e32 v135, v27, v135
	v_mul_f32_e32 v132, 0xbfb8aa3b, v132
	v_mul_f32_e32 v133, 0xbfb8aa3b, v133
	v_mul_f32_e32 v134, 0xbfb8aa3b, v134
	v_mul_f32_e32 v135, 0xbfb8aa3b, v135
	v_exp_f32_e32 v132, v132
	v_exp_f32_e32 v133, v133
	v_exp_f32_e32 v134, v134
	v_exp_f32_e32 v135, v135
	v_add_f32_e32 v132, 1.0, v132
	v_add_f32_e32 v133, 1.0, v133
	v_add_f32_e32 v139, 1.0, v134
	v_add_f32_e32 v140, 1.0, v135
	v_rcp_f32_e32 v134, v132
	v_rcp_f32_e32 v135, v133
	v_rcp_f32_e32 v132, v139
	v_rcp_f32_e32 v133, v140

; __device__ __forceinline__ float siluf(float v) { return v * __builtin_amdgcn_rcpf(1.f + __builtin_amdgcn_exp2f(-1.4426950408889634f * v)); }
; __device__ __forceinline__ float sigmf(float v) { return __builtin_amdgcn_rcpf(1.f + __builtin_amdgcn_exp2f(-1.4426950408889634f * v)); }
; #define G1_STG(mi_, ni_, v_) do { const int r_ = (mi_) * 16 + idx; const f32x4 t_ = (v_); u32x2 pk_; pk_.x = pk2(t_.x, t_.y); pk_.y = pk2(t_.z, t_.w); \
;         *(u32x2*)(wl + r_ * 128 + ((((ni_) * 2 + (kq >> 1)) ^ (r_ & 7)) * 16) + (kq & 1) * 8) = pk_; } while (0)
; __device__ void gemm1_phase(const Params& p, int l, int hb, unsigned char* smem) {
;     ...
;             for (int mi = 0; mi < 8; ++mi) {
; #pragma unroll
;                 for (int ni = 0; ni < 4; ++ni) {
;                     f32x4 v = acc[mi][ni];
;                     if (mode == 1) { v.x = siluf(v.x); v.y = siluf(v.y); v.z = siluf(v.z); v.w = siluf(v.w); }
;                     else if (mode == 2) { const f32x4 bb = *(const f32x4*)(bg + ni * 16); v.x = sigmf(v.x + bb.x); v.y = sigmf(v.y + bb.y); v.z = sigmf(v.z + bb.z); v.w = sigmf(v.w + bb.w); }
;                     G1_STG(mi, ni, v);
.LBB0_427:
	s_nop 0
	v_cvt_pk_bf16_f32 v134, v134, v135
	v_cvt_pk_bf16_f32 v135, v132, v133
	s_and_b64 vcc, exec, s[38:39]
	s_mov_b64 s[62:63], -1
	ds_write_b64 v136, v[134:135] offset:12288
	s_cbranch_vccnz .LBB0_431
	s_and_b64 vcc, exec, s[36:37]
	v_mov_b32_e32 v133, v23
	v_mov_b32_e32 v132, v22
	v_mov_b32_e32 v135, v21
	v_mov_b32_e32 v134, v20
	s_cbranch_vccnz .LBB0_430
	s_waitcnt vmcnt(0)
	v_mov_b32_e32 v132, v168
	v_mov_b32_e32 v133, v169
	v_mov_b32_e32 v134, v170
	v_mov_b32_e32 v135, v171
	v_add_f32_e32 v132, v20, v132
	v_add_f32_e32 v133, v21, v133
	v_add_f32_e32 v134, v22, v134
	v_add_f32_e32 v135, v23, v135
	v_mul_f32_e32 v132, 0xbfb8aa3b, v132
	v_mul_f32_e32 v133, 0xbfb8aa3b, v133
	v_mul_f32_e32 v134, 0xbfb8aa3b, v134
	v_mul_f32_e32 v135, 0xbfb8aa3b, v135
	v_exp_f32_e32 v132, v132
	v_exp_f32_e32 v133, v133
	v_exp_f32_e32 v134, v134
	v_exp_f32_e32 v135, v135
	v_add_f32_e32 v132, 1.0, v132
	v_add_f32_e32 v133, 1.0, v133
	v_add_f32_e32 v139, 1.0, v134
	v_add_f32_e32 v140, 1.0, v135
	v_rcp_f32_e32 v134, v132
	v_rcp_f32_e32 v135, v133
	v_rcp_f32_e32 v132, v139
	v_rcp_f32_e32 v133, v140

; __device__ __forceinline__ float siluf(float v) { return v * __builtin_amdgcn_rcpf(1.f + __builtin_amdgcn_exp2f(-1.4426950408889634f * v)); }
; __device__ __forceinline__ float sigmf(float v) { return __builtin_amdgcn_rcpf(1.f + __builtin_amdgcn_exp2f(-1.4426950408889634f * v)); }
; #define G1_STG(mi_, ni_, v_) do { const int r_ = (mi_) * 16 + idx; const f32x4 t_ = (v_); u32x2 pk_; pk_.x = pk2(t_.x, t_.y); pk_.y = pk2(t_.z, t_.w); \
;         *(u32x2*)(wl + r_ * 128 + ((((ni_) * 2 + (kq >> 1)) ^ (r_ & 7)) * 16) + (kq & 1) * 8) = pk_; } while (0)
; __device__ void gemm1_phase(const Params& p, int l, int hb, unsigned char* smem) {
;     ...
;             for (int mi = 0; mi < 8; ++mi) {
; #pragma unroll
;                 for (int ni = 0; ni < 4; ++ni) {
;                     f32x4 v = acc[mi][ni];
;                     if (mode == 1) { v.x = siluf(v.x); v.y = siluf(v.y); v.z = siluf(v.z); v.w = siluf(v.w); }
;                     else if (mode == 2) { const f32x4 bb = *(const f32x4*)(bg + ni * 16); v.x = sigmf(v.x + bb.x); v.y = sigmf(v.y + bb.y); v.z = sigmf(v.z + bb.z); v.w = sigmf(v.w + bb.w); }
;                     G1_STG(mi, ni, v);
.LBB0_433:
	s_nop 0
	v_cvt_pk_bf16_f32 v134, v134, v135
	v_cvt_pk_bf16_f32 v135, v132, v133
	s_and_b64 vcc, exec, s[38:39]
	s_mov_b64 s[62:63], -1
	ds_write_b64 v137, v[134:135] offset:12288
	s_cbranch_vccnz .LBB0_437
	s_and_b64 vcc, exec, s[36:37]
	v_mov_b32_e32 v133, v19
	v_mov_b32_e32 v132, v18
	v_mov_b32_e32 v135, v17
	v_mov_b32_e32 v134, v16
	s_cbranch_vccnz .LBB0_436
	s_waitcnt vmcnt(0)
	v_mov_b32_e32 v132, v172
	v_mov_b32_e32 v133, v173
	v_mov_b32_e32 v134, v174
	v_mov_b32_e32 v135, v175
	v_add_f32_e32 v132, v16, v132
	v_add_f32_e32 v133, v17, v133
	v_add_f32_e32 v134, v18, v134
	v_add_f32_e32 v135, v19, v135
	v_mul_f32_e32 v132, 0xbfb8aa3b, v132
	v_mul_f32_e32 v133, 0xbfb8aa3b, v133
	v_mul_f32_e32 v134, 0xbfb8aa3b, v134
	v_mul_f32_e32 v135, 0xbfb8aa3b, v135
	v_exp_f32_e32 v132, v132
	v_exp_f32_e32 v133, v133
	v_exp_f32_e32 v134, v134
	v_exp_f32_e32 v135, v135
	v_add_f32_e32 v132, 1.0, v132
	v_add_f32_e32 v133, 1.0, v133
	v_add_f32_e32 v139, 1.0, v134
	v_add_f32_e32 v140, 1.0, v135
	v_rcp_f32_e32 v134, v132
	v_rcp_f32_e32 v135, v133
	v_rcp_f32_e32 v132, v139
	v_rcp_f32_e32 v133, v140

; __device__ __forceinline__ float siluf(float v) { return v * __builtin_amdgcn_rcpf(1.f + __builtin_amdgcn_exp2f(-1.4426950408889634f * v)); }
; __device__ __forceinline__ float sigmf(float v) { return __builtin_amdgcn_rcpf(1.f + __builtin_amdgcn_exp2f(-1.4426950408889634f * v)); }
; #define G1_STG(mi_, ni_, v_) do { const int r_ = (mi_) * 16 + idx; const f32x4 t_ = (v_); u32x2 pk_; pk_.x = pk2(t_.x, t_.y); pk_.y = pk2(t_.z, t_.w); \
;         *(u32x2*)(wl + r_ * 128 + ((((ni_) * 2 + (kq >> 1)) ^ (r_ & 7)) * 16) + (kq & 1) * 8) = pk_; } while (0)
; __device__ void gemm1_phase(const Params& p, int l, int hb, unsigned char* smem) {
;     ...
;             for (int mi = 0; mi < 8; ++mi) {
; #pragma unroll
;                 for (int ni = 0; ni < 4; ++ni) {
;                     f32x4 v = acc[mi][ni];
;                     if (mode == 1) { v.x = siluf(v.x); v.y = siluf(v.y); v.z = siluf(v.z); v.w = siluf(v.w); }
;                     else if (mode == 2) { const f32x4 bb = *(const f32x4*)(bg + ni * 16); v.x = sigmf(v.x + bb.x); v.y = sigmf(v.y + bb.y); v.z = sigmf(v.z + bb.z); v.w = sigmf(v.w + bb.w); }
;                     G1_STG(mi, ni, v);
.LBB0_439:
	s_nop 0
	v_cvt_pk_bf16_f32 v134, v134, v135
	v_cvt_pk_bf16_f32 v135, v132, v133
	s_and_b64 vcc, exec, s[38:39]
	s_mov_b64 s[62:63], -1
	ds_write_b64 v138, v[134:135] offset:12288
	s_cbranch_vccnz .LBB0_443
	s_and_b64 vcc, exec, s[36:37]
	v_mov_b32_e32 v133, v15
	v_mov_b32_e32 v132, v14
	v_mov_b32_e32 v135, v13
	v_mov_b32_e32 v134, v12
	s_cbranch_vccnz .LBB0_442
	s_waitcnt vmcnt(0)
	v_mov_b32_e32 v132, v160
	v_mov_b32_e32 v133, v161
	v_mov_b32_e32 v134, v162
	v_mov_b32_e32 v135, v163
	v_add_f32_e32 v132, v12, v132
	v_add_f32_e32 v133, v13, v133
	v_add_f32_e32 v134, v14, v134
	v_add_f32_e32 v135, v15, v135
	v_mul_f32_e32 v132, 0xbfb8aa3b, v132
	v_mul_f32_e32 v133, 0xbfb8aa3b, v133
	v_mul_f32_e32 v134, 0xbfb8aa3b, v134
	v_mul_f32_e32 v135, 0xbfb8aa3b, v135
	v_exp_f32_e32 v132, v132
	v_exp_f32_e32 v133, v133
	v_exp_f32_e32 v134, v134
	v_exp_f32_e32 v135, v135
	v_add_f32_e32 v132, 1.0, v132
	v_add_f32_e32 v133, 1.0, v133
	v_add_f32_e32 v139, 1.0, v134
	v_add_f32_e32 v140, 1.0, v135
	v_rcp_f32_e32 v134, v132
	v_rcp_f32_e32 v135, v133
	v_rcp_f32_e32 v132, v139
	v_rcp_f32_e32 v133, v140

; __device__ __forceinline__ float siluf(float v) { return v * __builtin_amdgcn_rcpf(1.f + __builtin_amdgcn_exp2f(-1.4426950408889634f * v)); }
; __device__ __forceinline__ float sigmf(float v) { return __builtin_amdgcn_rcpf(1.f + __builtin_amdgcn_exp2f(-1.4426950408889634f * v)); }
; #define G1_STG(mi_, ni_, v_) do { const int r_ = (mi_) * 16 + idx; const f32x4 t_ = (v_); u32x2 pk_; pk_.x = pk2(t_.x, t_.y); pk_.y = pk2(t_.z, t_.w); \
;         *(u32x2*)(wl + r_ * 128 + ((((ni_) * 2 + (kq >> 1)) ^ (r_ & 7)) * 16) + (kq & 1) * 8) = pk_; } while (0)
; __device__ void gemm1_phase(const Params& p, int l, int hb, unsigned char* smem) {
;     ...
;             for (int mi = 0; mi < 8; ++mi) {
; #pragma unroll
;                 for (int ni = 0; ni < 4; ++ni) {
;                     f32x4 v = acc[mi][ni];
;                     if (mode == 1) { v.x = siluf(v.x); v.y = siluf(v.y); v.z = siluf(v.z); v.w = siluf(v.w); }
;                     else if (mode == 2) { const f32x4 bb = *(const f32x4*)(bg + ni * 16); v.x = sigmf(v.x + bb.x); v.y = sigmf(v.y + bb.y); v.z = sigmf(v.z + bb.z); v.w = sigmf(v.w + bb.w); }
;                     G1_STG(mi, ni, v);
.LBB0_445:
	s_nop 0
	v_cvt_pk_bf16_f32 v134, v134, v135
	v_cvt_pk_bf16_f32 v135, v132, v133
	s_and_b64 vcc, exec, s[38:39]
	s_mov_b64 s[62:63], -1
	ds_write_b64 v80, v[134:135] offset:14336
	s_cbranch_vccnz .LBB0_449
	s_and_b64 vcc, exec, s[36:37]
	v_mov_b32_e32 v133, v11
	v_mov_b32_e32 v132, v10
	v_mov_b32_e32 v135, v9
	v_mov_b32_e32 v134, v8
	s_cbranch_vccnz .LBB0_448
	s_waitcnt vmcnt(0)
	v_mov_b32_e32 v132, v164
	v_mov_b32_e32 v133, v165
	v_mov_b32_e32 v134, v166
	v_mov_b32_e32 v135, v167
	v_add_f32_e32 v80, v8, v132
	v_add_f32_e32 v132, v9, v133
	v_add_f32_e32 v133, v10, v134
	v_add_f32_e32 v134, v11, v135
	v_mul_f32_e32 v80, 0xbfb8aa3b, v80
	v_mul_f32_e32 v132, 0xbfb8aa3b, v132
	v_mul_f32_e32 v133, 0xbfb8aa3b, v133
	v_mul_f32_e32 v134, 0xbfb8aa3b, v134
	v_exp_f32_e32 v80, v80
	v_exp_f32_e32 v132, v132
	v_exp_f32_e32 v133, v133
	v_exp_f32_e32 v134, v134
	v_add_f32_e32 v80, 1.0, v80
	v_add_f32_e32 v132, 1.0, v132
	v_add_f32_e32 v133, 1.0, v133
	v_add_f32_e32 v139, 1.0, v134
	v_rcp_f32_e32 v134, v80
	v_rcp_f32_e32 v135, v132
	v_rcp_f32_e32 v132, v133
	v_rcp_f32_e32 v133, v139

; __device__ __forceinline__ float siluf(float v) { return v * __builtin_amdgcn_rcpf(1.f + __builtin_amdgcn_exp2f(-1.4426950408889634f * v)); }
; __device__ __forceinline__ float sigmf(float v) { return __builtin_amdgcn_rcpf(1.f + __builtin_amdgcn_exp2f(-1.4426950408889634f * v)); }
; #define G1_STG(mi_, ni_, v_) do { const int r_ = (mi_) * 16 + idx; const f32x4 t_ = (v_); u32x2 pk_; pk_.x = pk2(t_.x, t_.y); pk_.y = pk2(t_.z, t_.w); \
;         *(u32x2*)(wl + r_ * 128 + ((((ni_) * 2 + (kq >> 1)) ^ (r_ & 7)) * 16) + (kq & 1) * 8) = pk_; } while (0)
; __device__ void gemm1_phase(const Params& p, int l, int hb, unsigned char* smem) {
;     ...
;             for (int mi = 0; mi < 8; ++mi) {
; #pragma unroll
;                 for (int ni = 0; ni < 4; ++ni) {
;                     f32x4 v = acc[mi][ni];
;                     if (mode == 1) { v.x = siluf(v.x); v.y = siluf(v.y); v.z = siluf(v.z); v.w = siluf(v.w); }
;                     else if (mode == 2) { const f32x4 bb = *(const f32x4*)(bg + ni * 16); v.x = sigmf(v.x + bb.x); v.y = sigmf(v.y + bb.y); v.z = sigmf(v.z + bb.z); v.w = sigmf(v.w + bb.w); }
;                     G1_STG(mi, ni, v);
.LBB0_451:
	s_nop 0
	v_cvt_pk_bf16_f32 v134, v134, v135
	v_cvt_pk_bf16_f32 v135, v132, v133
	s_and_b64 vcc, exec, s[38:39]
	s_mov_b64 s[62:63], -1
	ds_write_b64 v136, v[134:135] offset:14336
	s_cbranch_vccnz .LBB0_455
	s_and_b64 vcc, exec, s[36:37]
	v_mov_b32_e32 v133, v7
	v_mov_b32_e32 v132, v6
	v_mov_b32_e32 v135, v5
	v_mov_b32_e32 v134, v4
	s_cbranch_vccnz .LBB0_454
	s_waitcnt vmcnt(0)
	v_mov_b32_e32 v132, v168
	v_mov_b32_e32 v133, v169
	v_mov_b32_e32 v134, v170
	v_mov_b32_e32 v135, v171
	v_add_f32_e32 v80, v4, v132
	v_add_f32_e32 v132, v5, v133
	v_add_f32_e32 v133, v6, v134
	v_add_f32_e32 v134, v7, v135
	v_mul_f32_e32 v80, 0xbfb8aa3b, v80
	v_mul_f32_e32 v132, 0xbfb8aa3b, v132
	v_mul_f32_e32 v133, 0xbfb8aa3b, v133
	v_mul_f32_e32 v134, 0xbfb8aa3b, v134
	v_exp_f32_e32 v80, v80
	v_exp_f32_e32 v132, v132
	v_exp_f32_e32 v133, v133
	v_exp_f32_e32 v134, v134
	v_add_f32_e32 v80, 1.0, v80
	v_add_f32_e32 v132, 1.0, v132
	v_add_f32_e32 v133, 1.0, v133
	v_add_f32_e32 v136, 1.0, v134
	v_rcp_f32_e32 v134, v80
	v_rcp_f32_e32 v135, v132
	v_rcp_f32_e32 v132, v133
	v_rcp_f32_e32 v133, v136

; __device__ __forceinline__ float siluf(float v) { return v * __builtin_amdgcn_rcpf(1.f + __builtin_amdgcn_exp2f(-1.4426950408889634f * v)); }
; __device__ __forceinline__ float sigmf(float v) { return __builtin_amdgcn_rcpf(1.f + __builtin_amdgcn_exp2f(-1.4426950408889634f * v)); }
; #define G1_STG(mi_, ni_, v_) do { const int r_ = (mi_) * 16 + idx; const f32x4 t_ = (v_); u32x2 pk_; pk_.x = pk2(t_.x, t_.y); pk_.y = pk2(t_.z, t_.w); \
;         *(u32x2*)(wl + r_ * 128 + ((((ni_) * 2 + (kq >> 1)) ^ (r_ & 7)) * 16) + (kq & 1) * 8) = pk_; } while (0)
; __device__ void gemm1_phase(const Params& p, int l, int hb, unsigned char* smem) {
;     ...
;             for (int mi = 0; mi < 8; ++mi) {
; #pragma unroll
;                 for (int ni = 0; ni < 4; ++ni) {
;                     f32x4 v = acc[mi][ni];
;                     if (mode == 1) { v.x = siluf(v.x); v.y = siluf(v.y); v.z = siluf(v.z); v.w = siluf(v.w); }
;                     else if (mode == 2) { const f32x4 bb = *(const f32x4*)(bg + ni * 16); v.x = sigmf(v.x + bb.x); v.y = sigmf(v.y + bb.y); v.z = sigmf(v.z + bb.z); v.w = sigmf(v.w + bb.w); }
;                     G1_STG(mi, ni, v);
.LBB0_457:
	s_nop 0
	v_cvt_pk_bf16_f32 v134, v134, v135
	v_cvt_pk_bf16_f32 v135, v132, v133
	s_and_b64 vcc, exec, s[38:39]
	s_mov_b64 s[38:39], -1
	ds_write_b64 v137, v[134:135] offset:14336
	s_cbranch_vccnz .LBB0_461
	s_and_b64 vcc, exec, s[36:37]
	v_mov_b32_e32 v133, v3
	v_mov_b32_e32 v132, v2
	v_mov_b32_e32 v135, v1
	v_mov_b32_e32 v134, v0
	s_cbranch_vccnz .LBB0_460
	s_waitcnt vmcnt(0)
	v_mov_b32_e32 v130, v172
	v_mov_b32_e32 v131, v173
	v_mov_b32_e32 v132, v174
	v_mov_b32_e32 v133, v175
	v_add_f32_e32 v80, v0, v130
	v_add_f32_e32 v130, v1, v131
	v_add_f32_e32 v131, v2, v132
	v_add_f32_e32 v132, v3, v133
	v_mul_f32_e32 v80, 0xbfb8aa3b, v80
	v_mul_f32_e32 v130, 0xbfb8aa3b, v130
	v_mul_f32_e32 v131, 0xbfb8aa3b, v131
	v_mul_f32_e32 v132, 0xbfb8aa3b, v132
	v_exp_f32_e32 v80, v80
	v_exp_f32_e32 v130, v130
	v_exp_f32_e32 v131, v131
	v_exp_f32_e32 v132, v132
	v_add_f32_e32 v80, 1.0, v80
	v_add_f32_e32 v130, 1.0, v130
	v_add_f32_e32 v131, 1.0, v131
	v_add_f32_e32 v133, 1.0, v132
	v_rcp_f32_e32 v134, v80
	v_rcp_f32_e32 v135, v130
	v_rcp_f32_e32 v132, v131
	v_rcp_f32_e32 v133, v133
